# v21 + FF2 A-operand DMA pieces first + mid-block setprio pairs removed
# baseline (speedup 1.0000x reference)
.LBB0_33:
	s_add_i32 s63, 0, 0x10000
	s_add_i32 s64, 0, 0x14000
	v_add_u32_e32 v64, s63, v78
	ds_read_b128 v[138:141], v64
	ds_read_b128 v[142:145], v64 offset:1024
	ds_read_b128 v[146:149], v64 offset:2048
	ds_read_b128 v[150:153], v64 offset:3072
	v_add_u32_e32 v64, s64, v78
	ds_read_b128 v[154:157], v64
	ds_read_b128 v[158:161], v64 offset:1024
	ds_read_b128 v[162:165], v64 offset:2048
	ds_read_b128 v[166:169], v64 offset:3072
	s_add_u32 s60, s56, s92
	s_addc_u32 s61, s57, s93
	s_add_u32 s2, s60, 0x2500100
	s_addc_u32 s3, s61, 0
	s_add_u32 s54, s58, s92
	s_addc_u32 s55, s59, s93
	s_cmpk_eq_i32 s92, 0x1f00
	s_cselect_b32 s3, s47, s3
	s_cselect_b32 s2, s46, s2
	s_cselect_b32 s55, s41, s55
	s_cselect_b32 s54, s40, s54
	v_mov_b32_e32 v64, v74
	ds_read_b128 v[170:173], v79
	ds_read_b128 v[174:177], v79 offset:1024
	ds_read_b128 v[178:181], v79 offset:2048
	ds_read_b128 v[182:185], v79 offset:3072
	ds_read_b128 v[190:193], v79 offset:4096
	ds_read_b128 v[194:197], v79 offset:5120
	ds_read_b128 v[198:201], v79 offset:6144
	ds_read_b128 v[214:217], v79 offset:7168
	s_add_i32 m0, s17, 0xc000
	v_lshl_add_u64 v[80:81], s[60:61], 0, v[64:65]
	v_lshl_add_u64 v[80:81], v[80:81], 0, s[66:67]
	v_mov_b32_e32 v64, v76
	global_load_lds_dwordx4 v[80:81], off
	s_add_i32 m0, s17, 0xe000
	v_lshl_add_u64 v[80:81], s[60:61], 0, v[64:65]
	v_lshl_add_u64 v[80:81], v[80:81], 0, s[66:67]
	global_load_lds_dwordx4 v[80:81], off
	s_waitcnt vmcnt(8)
	s_waitcnt lgkmcnt(0)
	s_barrier
	s_setprio 1
	s_waitcnt lgkmcnt(0)
	v_mfma_f32_16x16x32_bf16 v[70:73], v[138:141], v[170:173], v[70:73]
	v_mfma_f32_16x16x32_bf16 v[56:59], v[146:149], v[170:173], v[56:59]
	v_mfma_f32_16x16x32_bf16 v[126:129], v[138:141], v[178:181], v[126:129]
	v_mfma_f32_16x16x32_bf16 v[122:125], v[146:149], v[178:181], v[122:125]
	v_mfma_f32_16x16x32_bf16 v[110:113], v[138:141], v[190:193], v[110:113]
	v_mfma_f32_16x16x32_bf16 v[106:109], v[146:149], v[190:193], v[106:109]
	v_mfma_f32_16x16x32_bf16 v[94:97], v[138:141], v[198:201], v[94:97]
	v_mfma_f32_16x16x32_bf16 v[90:93], v[146:149], v[198:201], v[90:93]
	v_mfma_f32_16x16x32_bf16 v[70:73], v[142:145], v[174:177], v[70:73]
	v_mfma_f32_16x16x32_bf16 v[56:59], v[150:153], v[174:177], v[56:59]
	v_mfma_f32_16x16x32_bf16 v[126:129], v[142:145], v[182:185], v[126:129]
	v_mfma_f32_16x16x32_bf16 v[122:125], v[150:153], v[182:185], v[122:125]
	v_mfma_f32_16x16x32_bf16 v[110:113], v[142:145], v[194:197], v[110:113]
	v_mfma_f32_16x16x32_bf16 v[106:109], v[150:153], v[194:197], v[106:109]
	v_mfma_f32_16x16x32_bf16 v[94:97], v[142:145], v[214:217], v[94:97]
	v_mfma_f32_16x16x32_bf16 v[90:93], v[150:153], v[214:217], v[90:93]
	v_mfma_f32_16x16x32_bf16 v[134:137], v[154:157], v[170:173], v[134:137]
	v_mfma_f32_16x16x32_bf16 v[130:133], v[162:165], v[170:173], v[130:133]
	v_mfma_f32_16x16x32_bf16 v[118:121], v[154:157], v[178:181], v[118:121]
	v_mfma_f32_16x16x32_bf16 v[114:117], v[162:165], v[178:181], v[114:117]
	v_mfma_f32_16x16x32_bf16 v[102:105], v[154:157], v[190:193], v[102:105]
	v_mfma_f32_16x16x32_bf16 v[98:101], v[162:165], v[190:193], v[98:101]
	v_mfma_f32_16x16x32_bf16 v[86:89], v[154:157], v[198:201], v[86:89]
	v_mfma_f32_16x16x32_bf16 v[80:83], v[162:165], v[198:201], v[82:85]
	v_mfma_f32_16x16x32_bf16 v[134:137], v[158:161], v[174:177], v[134:137]
	v_mfma_f32_16x16x32_bf16 v[130:133], v[166:169], v[174:177], v[130:133]
	v_mfma_f32_16x16x32_bf16 v[118:121], v[158:161], v[182:185], v[118:121]
	v_mfma_f32_16x16x32_bf16 v[114:117], v[166:169], v[182:185], v[114:117]
	v_mfma_f32_16x16x32_bf16 v[102:105], v[158:161], v[194:197], v[102:105]
	v_mfma_f32_16x16x32_bf16 v[98:101], v[166:169], v[194:197], v[98:101]
	v_mfma_f32_16x16x32_bf16 v[86:89], v[158:161], v[214:217], v[86:89]
	v_mfma_f32_16x16x32_bf16 v[80:83], v[166:169], v[214:217], v[80:83]
	s_setprio 0
	s_barrier
	v_mov_b32_e32 v64, v74
	s_mov_b32 m0, s17
	s_nop 0
	global_load_lds_dwordx4 v64, s[2:3]
	v_mov_b32_e32 v64, v76
	s_mov_b32 m0, s22
	s_nop 0
	global_load_lds_dwordx4 v64, s[2:3]
	v_mov_b32_e32 v64, v75
	s_add_i32 s60, s63, s11
	ds_read_b128 v[170:173], v79 offset:16384
	ds_read_b128 v[174:177], v79 offset:17408
	ds_read_b128 v[178:181], v79 offset:18432
	ds_read_b128 v[182:185], v79 offset:19456
	ds_read_b128 v[190:193], v79 offset:20480
	ds_read_b128 v[194:197], v79 offset:21504
	ds_read_b128 v[198:201], v79 offset:22528
	ds_read_b128 v[214:217], v79 offset:23552
	s_mov_b32 m0, s60
	s_nop 0
	global_load_lds_dwordx4 v64, s[54:55]
	v_mov_b32_e32 v64, v77
	s_add_i32 m0, s60, 0x2000
	s_add_u32 s60, s54, 0x100000
	global_load_lds_dwordx4 v64, s[54:55]
	s_addc_u32 s61, s55, 0
	v_mov_b32_e32 v64, v75
	s_add_i32 s63, s64, s11
	s_mov_b32 m0, s63
	s_nop 0
	global_load_lds_dwordx4 v64, s[60:61]
	v_mov_b32_e32 v64, v77
	s_add_i32 m0, s63, 0x2000
	s_nop 0
	global_load_lds_dwordx4 v64, s[60:61]
	s_waitcnt vmcnt(8)
	s_waitcnt lgkmcnt(0)
	s_barrier
	s_setprio 1
	s_waitcnt lgkmcnt(0)
	v_mfma_f32_16x16x32_bf16 v[66:69], v[138:141], v[170:173], v[66:69]
	v_mfma_f32_16x16x32_bf16 v[60:63], v[146:149], v[170:173], v[60:63]
	v_mfma_f32_16x16x32_bf16 v[44:47], v[138:141], v[178:181], v[44:47]
	v_mfma_f32_16x16x32_bf16 v[40:43], v[146:149], v[178:181], v[40:43]
	v_mfma_f32_16x16x32_bf16 v[28:31], v[138:141], v[190:193], v[28:31]
	v_mfma_f32_16x16x32_bf16 v[24:27], v[146:149], v[190:193], v[24:27]
	v_mfma_f32_16x16x32_bf16 v[12:15], v[138:141], v[198:201], v[12:15]
	v_mfma_f32_16x16x32_bf16 v[8:11], v[146:149], v[198:201], v[8:11]
	v_mfma_f32_16x16x32_bf16 v[66:69], v[142:145], v[174:177], v[66:69]
	v_mfma_f32_16x16x32_bf16 v[60:63], v[150:153], v[174:177], v[60:63]
	v_mfma_f32_16x16x32_bf16 v[44:47], v[142:145], v[182:185], v[44:47]
	v_mfma_f32_16x16x32_bf16 v[40:43], v[150:153], v[182:185], v[40:43]
	v_mfma_f32_16x16x32_bf16 v[28:31], v[142:145], v[194:197], v[28:31]
	v_mfma_f32_16x16x32_bf16 v[24:27], v[150:153], v[194:197], v[24:27]
	v_mfma_f32_16x16x32_bf16 v[12:15], v[142:145], v[214:217], v[12:15]
	v_mfma_f32_16x16x32_bf16 v[8:11], v[150:153], v[214:217], v[8:11]
	v_mfma_f32_16x16x32_bf16 v[52:55], v[154:157], v[170:173], v[52:55]
	v_mfma_f32_16x16x32_bf16 v[48:51], v[162:165], v[170:173], v[48:51]
	v_mfma_f32_16x16x32_bf16 v[36:39], v[154:157], v[178:181], v[36:39]
	v_mfma_f32_16x16x32_bf16 v[32:35], v[162:165], v[178:181], v[32:35]
	v_mfma_f32_16x16x32_bf16 v[20:23], v[154:157], v[190:193], v[20:23]
	v_mfma_f32_16x16x32_bf16 v[16:19], v[162:165], v[190:193], v[16:19]
	v_mfma_f32_16x16x32_bf16 v[4:7], v[154:157], v[198:201], v[4:7]
	v_mfma_f32_16x16x32_bf16 v[0:3], v[162:165], v[198:201], v[0:3]
	v_mfma_f32_16x16x32_bf16 v[52:55], v[158:161], v[174:177], v[52:55]
	v_mfma_f32_16x16x32_bf16 v[48:51], v[166:169], v[174:177], v[48:51]
	v_mfma_f32_16x16x32_bf16 v[36:39], v[158:161], v[182:185], v[36:39]
	v_mfma_f32_16x16x32_bf16 v[32:35], v[166:169], v[182:185], v[32:35]
	v_mfma_f32_16x16x32_bf16 v[20:23], v[158:161], v[194:197], v[20:23]
	v_mfma_f32_16x16x32_bf16 v[16:19], v[166:169], v[194:197], v[16:19]
	v_mfma_f32_16x16x32_bf16 v[4:7], v[158:161], v[214:217], v[4:7]
	v_mfma_f32_16x16x32_bf16 v[0:3], v[166:169], v[214:217], v[0:3]
	s_setprio 0
	s_barrier
	s_add_i32 s63, 0, 0x18000
	v_add_u32_e32 v64, s63, v78
	s_add_i32 s64, 0, 0x1c000
	ds_read_b128 v[138:141], v64
	ds_read_b128 v[142:145], v64 offset:1024
	ds_read_b128 v[146:149], v64 offset:2048
	ds_read_b128 v[150:153], v64 offset:3072
	v_add_u32_e32 v64, s64, v78
	ds_read_b128 v[154:157], v64
	ds_read_b128 v[158:161], v64 offset:1024
	ds_read_b128 v[162:165], v64 offset:2048
	ds_read_b128 v[166:169], v64 offset:3072
	s_add_u32 s60, s2, 0x100000
	v_mov_b32_e32 v64, v74
	s_mov_b32 m0, s49
	ds_read_b128 v[170:173], v79 offset:32768
	ds_read_b128 v[174:177], v79 offset:33792
	ds_read_b128 v[178:181], v79 offset:34816
	ds_read_b128 v[182:185], v79 offset:35840
	ds_read_b128 v[190:193], v79 offset:36864
	ds_read_b128 v[194:197], v79 offset:37888
	ds_read_b128 v[198:201], v79 offset:38912
	ds_read_b128 v[214:217], v79 offset:39936
	s_addc_u32 s61, s3, 0
	s_nop 0
	global_load_lds_dwordx4 v64, s[60:61]
	v_mov_b32_e32 v64, v76
	s_mov_b32 m0, s50
	s_nop 0
	global_load_lds_dwordx4 v64, s[60:61]
	s_waitcnt vmcnt(8)
	s_waitcnt lgkmcnt(0)
	s_barrier
	s_setprio 1
	s_waitcnt lgkmcnt(0)
	v_mfma_f32_16x16x32_bf16 v[70:73], v[138:141], v[170:173], v[70:73]
	v_mfma_f32_16x16x32_bf16 v[56:59], v[146:149], v[170:173], v[56:59]
	v_mfma_f32_16x16x32_bf16 v[126:129], v[138:141], v[178:181], v[126:129]
	v_mfma_f32_16x16x32_bf16 v[122:125], v[146:149], v[178:181], v[122:125]
	v_mfma_f32_16x16x32_bf16 v[110:113], v[138:141], v[190:193], v[110:113]
	v_mfma_f32_16x16x32_bf16 v[106:109], v[146:149], v[190:193], v[106:109]
	v_mfma_f32_16x16x32_bf16 v[94:97], v[138:141], v[198:201], v[94:97]
	v_mfma_f32_16x16x32_bf16 v[90:93], v[146:149], v[198:201], v[90:93]
	v_mfma_f32_16x16x32_bf16 v[70:73], v[142:145], v[174:177], v[70:73]
	v_mfma_f32_16x16x32_bf16 v[56:59], v[150:153], v[174:177], v[56:59]
	v_mfma_f32_16x16x32_bf16 v[126:129], v[142:145], v[182:185], v[126:129]
	v_mfma_f32_16x16x32_bf16 v[122:125], v[150:153], v[182:185], v[122:125]
	v_mfma_f32_16x16x32_bf16 v[110:113], v[142:145], v[194:197], v[110:113]
	v_mfma_f32_16x16x32_bf16 v[106:109], v[150:153], v[194:197], v[106:109]
	v_mfma_f32_16x16x32_bf16 v[94:97], v[142:145], v[214:217], v[94:97]
	v_mfma_f32_16x16x32_bf16 v[90:93], v[150:153], v[214:217], v[90:93]
	v_mfma_f32_16x16x32_bf16 v[134:137], v[154:157], v[170:173], v[134:137]
	v_mfma_f32_16x16x32_bf16 v[130:133], v[162:165], v[170:173], v[130:133]
	v_mfma_f32_16x16x32_bf16 v[118:121], v[154:157], v[178:181], v[118:121]
	v_mfma_f32_16x16x32_bf16 v[114:117], v[162:165], v[178:181], v[114:117]
	v_mfma_f32_16x16x32_bf16 v[102:105], v[154:157], v[190:193], v[102:105]
	v_mfma_f32_16x16x32_bf16 v[98:101], v[162:165], v[190:193], v[98:101]
	v_mfma_f32_16x16x32_bf16 v[84:87], v[154:157], v[198:201], v[86:89]
	v_mfma_f32_16x16x32_bf16 v[80:83], v[162:165], v[198:201], v[80:83]
	v_mfma_f32_16x16x32_bf16 v[134:137], v[158:161], v[174:177], v[134:137]
	v_mfma_f32_16x16x32_bf16 v[130:133], v[166:169], v[174:177], v[130:133]
	v_mfma_f32_16x16x32_bf16 v[118:121], v[158:161], v[182:185], v[118:121]
	v_mfma_f32_16x16x32_bf16 v[114:117], v[166:169], v[182:185], v[114:117]
	v_mfma_f32_16x16x32_bf16 v[102:105], v[158:161], v[194:197], v[102:105]
	v_mfma_f32_16x16x32_bf16 v[98:101], v[166:169], v[194:197], v[98:101]
	v_mfma_f32_16x16x32_bf16 v[86:89], v[158:161], v[214:217], v[84:87]
	v_mfma_f32_16x16x32_bf16 v[82:85], v[166:169], v[214:217], v[80:83]
	s_setprio 0
	s_barrier
	v_mov_b32_e32 v64, v74
	s_mov_b32 m0, s52
	v_lshl_add_u64 v[80:81], s[2:3], 0, v[64:65]
	v_lshl_add_u64 v[80:81], v[80:81], 0, s[24:25]
	v_mov_b32_e32 v64, v76
	global_load_lds_dwordx4 v[80:81], off
	s_mov_b32 m0, s53
	v_lshl_add_u64 v[80:81], s[2:3], 0, v[64:65]
	v_lshl_add_u64 v[80:81], v[80:81], 0, s[24:25]
	global_load_lds_dwordx4 v[80:81], off
	v_mov_b32_e32 v64, v75
	ds_read_b128 v[170:173], v79 offset:49152
	ds_read_b128 v[174:177], v79 offset:50176
	ds_read_b128 v[178:181], v79 offset:51200
	ds_read_b128 v[182:185], v79 offset:52224
	ds_read_b128 v[190:193], v79 offset:53248
	ds_read_b128 v[194:197], v79 offset:54272
	ds_read_b128 v[198:201], v79 offset:55296
	ds_read_b128 v[214:217], v79 offset:56320
	s_add_i32 s60, s63, s11
	v_lshl_add_u64 v[80:81], s[54:55], 0, v[64:65]
	v_lshl_add_u64 v[80:81], v[80:81], 0, s[24:25]
	s_mov_b32 m0, s60
	v_mov_b32_e32 v64, v77
	global_load_lds_dwordx4 v[80:81], off
	s_add_i32 m0, s60, 0x2000
	s_nop 0
	v_lshl_add_u64 v[80:81], s[54:55], 0, v[64:65]
	s_add_u32 s54, s54, 0x100080
	v_lshl_add_u64 v[80:81], v[80:81], 0, s[24:25]
	s_addc_u32 s55, s55, 0
	v_mov_b32_e32 v64, v75
	s_add_i32 s60, s64, s11
	global_load_lds_dwordx4 v[80:81], off
	s_mov_b32 m0, s60
	s_nop 0
	global_load_lds_dwordx4 v64, s[54:55]
	v_mov_b32_e32 v64, v77
	s_add_i32 m0, s60, 0x2000
	s_nop 0
	global_load_lds_dwordx4 v64, s[54:55]
	s_waitcnt vmcnt(8)
	s_waitcnt lgkmcnt(0)
	s_barrier
	s_setprio 1
	s_waitcnt lgkmcnt(0)
	v_mfma_f32_16x16x32_bf16 v[66:69], v[138:141], v[170:173], v[66:69]
	v_mfma_f32_16x16x32_bf16 v[60:63], v[146:149], v[170:173], v[60:63]
	v_mfma_f32_16x16x32_bf16 v[44:47], v[138:141], v[178:181], v[44:47]
	v_mfma_f32_16x16x32_bf16 v[40:43], v[146:149], v[178:181], v[40:43]
	v_mfma_f32_16x16x32_bf16 v[28:31], v[138:141], v[190:193], v[28:31]
	v_mfma_f32_16x16x32_bf16 v[24:27], v[146:149], v[190:193], v[24:27]
	v_mfma_f32_16x16x32_bf16 v[12:15], v[138:141], v[198:201], v[12:15]
	v_mfma_f32_16x16x32_bf16 v[8:11], v[146:149], v[198:201], v[8:11]
	v_mfma_f32_16x16x32_bf16 v[66:69], v[142:145], v[174:177], v[66:69]
	v_mfma_f32_16x16x32_bf16 v[60:63], v[150:153], v[174:177], v[60:63]
	v_mfma_f32_16x16x32_bf16 v[44:47], v[142:145], v[182:185], v[44:47]
	v_mfma_f32_16x16x32_bf16 v[40:43], v[150:153], v[182:185], v[40:43]
	v_mfma_f32_16x16x32_bf16 v[28:31], v[142:145], v[194:197], v[28:31]
	v_mfma_f32_16x16x32_bf16 v[24:27], v[150:153], v[194:197], v[24:27]
	v_mfma_f32_16x16x32_bf16 v[12:15], v[142:145], v[214:217], v[12:15]
	v_mfma_f32_16x16x32_bf16 v[8:11], v[150:153], v[214:217], v[8:11]
	v_mfma_f32_16x16x32_bf16 v[52:55], v[154:157], v[170:173], v[52:55]
	v_mfma_f32_16x16x32_bf16 v[48:51], v[162:165], v[170:173], v[48:51]
	v_mfma_f32_16x16x32_bf16 v[36:39], v[154:157], v[178:181], v[36:39]
	v_mfma_f32_16x16x32_bf16 v[32:35], v[162:165], v[178:181], v[32:35]
	v_mfma_f32_16x16x32_bf16 v[20:23], v[154:157], v[190:193], v[20:23]
	v_mfma_f32_16x16x32_bf16 v[16:19], v[162:165], v[190:193], v[16:19]
	v_mfma_f32_16x16x32_bf16 v[4:7], v[154:157], v[198:201], v[4:7]
	v_mfma_f32_16x16x32_bf16 v[0:3], v[162:165], v[198:201], v[0:3]
	v_mfma_f32_16x16x32_bf16 v[52:55], v[158:161], v[174:177], v[52:55]
	v_mfma_f32_16x16x32_bf16 v[48:51], v[166:169], v[174:177], v[48:51]
	v_mfma_f32_16x16x32_bf16 v[36:39], v[158:161], v[182:185], v[36:39]
	v_mfma_f32_16x16x32_bf16 v[32:35], v[166:169], v[182:185], v[32:35]
	v_mfma_f32_16x16x32_bf16 v[20:23], v[158:161], v[194:197], v[20:23]
	v_mfma_f32_16x16x32_bf16 v[16:19], v[166:169], v[194:197], v[16:19]
	v_mfma_f32_16x16x32_bf16 v[4:7], v[158:161], v[214:217], v[4:7]
	v_mfma_f32_16x16x32_bf16 v[0:3], v[166:169], v[214:217], v[0:3]
	s_setprio 0
	s_barrier
	s_add_i32 s62, s62, 2
	s_add_u32 s92, s92, 0x100
	s_addc_u32 s93, s93, 0
	s_cmp_gt_u32 s62, 61
	s_cbranch_scc0 .LBB0_33
	s_cmp_lt_u32 s48, 4
	s_cbranch_scc0 .LBB0_36
	s_barrier

.LBB0_80:
	s_add_i32 s60, 0, 0x10000
	s_add_i32 s70, 0, 0x14000
	v_add_u32_e32 v64, s60, v136
	ds_read_b128 v[138:141], v64
	ds_read_b128 v[142:145], v64 offset:1024
	ds_read_b128 v[146:149], v64 offset:2048
	ds_read_b128 v[150:153], v64 offset:3072
	v_add_u32_e32 v64, s70, v136
	ds_read_b128 v[154:157], v64
	ds_read_b128 v[158:161], v64 offset:1024
	ds_read_b128 v[162:165], v64 offset:2048
	ds_read_b128 v[166:169], v64 offset:3072
	s_add_u32 s2, s94, 0xfffc0080
	s_addc_u32 s3, s95, -1
	s_cmp_eq_u32 s69, 12
	s_cselect_b32 s3, s63, s3
	s_cselect_b32 s2, s64, s2
	s_cselect_b32 s55, s65, s68
	s_cselect_b32 s54, s66, s67
	v_mov_b32_e32 v64, v132
	ds_read_b128 v[170:173], v137
	ds_read_b128 v[174:177], v137 offset:1024
	ds_read_b128 v[178:181], v137 offset:2048
	ds_read_b128 v[182:185], v137 offset:3072
	ds_read_b128 v[190:193], v137 offset:4096
	ds_read_b128 v[194:197], v137 offset:5120
	ds_read_b128 v[198:201], v137 offset:6144
	ds_read_b128 v[214:217], v137 offset:7168
	s_add_i32 m0, s50, 0xc000
	s_nop 0
	global_load_lds_dwordx4 v64, s[94:95]
	v_mov_b32_e32 v64, v134
	s_add_i32 m0, s50, 0xe000
	s_nop 0
	global_load_lds_dwordx4 v64, s[94:95]
	s_waitcnt vmcnt(8)
	s_waitcnt lgkmcnt(0)
	s_barrier
	s_setprio 1
	s_waitcnt lgkmcnt(0)
	v_mfma_f32_16x16x32_bf16 v[126:129], v[138:141], v[170:173], v[126:129]
	v_mfma_f32_16x16x32_bf16 v[122:125], v[146:149], v[170:173], v[122:125]
	v_mfma_f32_16x16x32_bf16 v[110:113], v[138:141], v[178:181], v[110:113]
	v_mfma_f32_16x16x32_bf16 v[106:109], v[146:149], v[178:181], v[106:109]
	v_mfma_f32_16x16x32_bf16 v[94:97], v[138:141], v[190:193], v[94:97]
	v_mfma_f32_16x16x32_bf16 v[90:93], v[146:149], v[190:193], v[90:93]
	v_mfma_f32_16x16x32_bf16 v[78:81], v[138:141], v[198:201], v[78:81]
	v_mfma_f32_16x16x32_bf16 v[74:77], v[146:149], v[198:201], v[74:77]
	v_mfma_f32_16x16x32_bf16 v[126:129], v[142:145], v[174:177], v[126:129]
	v_mfma_f32_16x16x32_bf16 v[122:125], v[150:153], v[174:177], v[122:125]
	v_mfma_f32_16x16x32_bf16 v[110:113], v[142:145], v[182:185], v[110:113]
	v_mfma_f32_16x16x32_bf16 v[106:109], v[150:153], v[182:185], v[106:109]
	v_mfma_f32_16x16x32_bf16 v[94:97], v[142:145], v[194:197], v[94:97]
	v_mfma_f32_16x16x32_bf16 v[90:93], v[150:153], v[194:197], v[90:93]
	v_mfma_f32_16x16x32_bf16 v[78:81], v[142:145], v[214:217], v[78:81]
	v_mfma_f32_16x16x32_bf16 v[74:77], v[150:153], v[214:217], v[74:77]
	v_mfma_f32_16x16x32_bf16 v[118:121], v[154:157], v[170:173], v[118:121]
	v_mfma_f32_16x16x32_bf16 v[114:117], v[162:165], v[170:173], v[114:117]
	v_mfma_f32_16x16x32_bf16 v[102:105], v[154:157], v[178:181], v[102:105]
	v_mfma_f32_16x16x32_bf16 v[98:101], v[162:165], v[178:181], v[98:101]
	v_mfma_f32_16x16x32_bf16 v[86:89], v[154:157], v[190:193], v[86:89]
	v_mfma_f32_16x16x32_bf16 v[82:85], v[162:165], v[190:193], v[82:85]
	v_mfma_f32_16x16x32_bf16 v[70:73], v[154:157], v[198:201], v[70:73]
	v_mfma_f32_16x16x32_bf16 v[66:69], v[162:165], v[198:201], v[66:69]
	v_mfma_f32_16x16x32_bf16 v[118:121], v[158:161], v[174:177], v[118:121]
	v_mfma_f32_16x16x32_bf16 v[114:117], v[166:169], v[174:177], v[114:117]
	v_mfma_f32_16x16x32_bf16 v[102:105], v[158:161], v[182:185], v[102:105]
	v_mfma_f32_16x16x32_bf16 v[98:101], v[166:169], v[182:185], v[98:101]
	v_mfma_f32_16x16x32_bf16 v[86:89], v[158:161], v[194:197], v[86:89]
	v_mfma_f32_16x16x32_bf16 v[82:85], v[166:169], v[194:197], v[82:85]
	v_mfma_f32_16x16x32_bf16 v[70:73], v[158:161], v[214:217], v[70:73]
	v_mfma_f32_16x16x32_bf16 v[66:69], v[166:169], v[214:217], v[66:69]
	s_setprio 0
	s_barrier
	v_mov_b32_e32 v64, v133
	s_add_i32 s60, s60, s49
	ds_read_b128 v[170:173], v137 offset:16384
	ds_read_b128 v[174:177], v137 offset:17408
	ds_read_b128 v[178:181], v137 offset:18432
	ds_read_b128 v[182:185], v137 offset:19456
	ds_read_b128 v[190:193], v137 offset:20480
	ds_read_b128 v[194:197], v137 offset:21504
	ds_read_b128 v[198:201], v137 offset:22528
	ds_read_b128 v[214:217], v137 offset:23552
	s_mov_b32 m0, s60
	s_nop 0
	global_load_lds_dwordx4 v64, s[54:55]
	v_mov_b32_e32 v64, v135
	s_add_i32 m0, s60, 0x2000
	s_add_u32 s60, s54, 0x40000
	global_load_lds_dwordx4 v64, s[54:55]
	s_addc_u32 s61, s55, 0
	v_mov_b32_e32 v64, v133
	s_add_i32 s70, s70, s49
	s_mov_b32 m0, s70
	s_nop 0
	global_load_lds_dwordx4 v64, s[60:61]
	v_mov_b32_e32 v64, v135
	s_add_i32 m0, s70, 0x2000
	s_nop 0
	global_load_lds_dwordx4 v64, s[60:61]
	v_mov_b32_e32 v64, v132
	s_mov_b32 m0, s50
	s_nop 0
	global_load_lds_dwordx4 v64, s[2:3]
	v_mov_b32_e32 v64, v134
	s_mov_b32 m0, s51
	s_nop 0
	global_load_lds_dwordx4 v64, s[2:3]
	s_waitcnt vmcnt(8)
	s_waitcnt lgkmcnt(0)
	s_barrier
	s_setprio 1
	s_waitcnt lgkmcnt(0)
	v_mfma_f32_16x16x32_bf16 v[60:63], v[138:141], v[170:173], v[60:63]
	v_mfma_f32_16x16x32_bf16 v[56:59], v[146:149], v[170:173], v[56:59]
	v_mfma_f32_16x16x32_bf16 v[44:47], v[138:141], v[178:181], v[44:47]
	v_mfma_f32_16x16x32_bf16 v[40:43], v[146:149], v[178:181], v[40:43]
	v_mfma_f32_16x16x32_bf16 v[28:31], v[138:141], v[190:193], v[28:31]
	v_mfma_f32_16x16x32_bf16 v[24:27], v[146:149], v[190:193], v[24:27]
	v_mfma_f32_16x16x32_bf16 v[12:15], v[138:141], v[198:201], v[12:15]
	v_mfma_f32_16x16x32_bf16 v[8:11], v[146:149], v[198:201], v[8:11]
	v_mfma_f32_16x16x32_bf16 v[60:63], v[142:145], v[174:177], v[60:63]
	v_mfma_f32_16x16x32_bf16 v[56:59], v[150:153], v[174:177], v[56:59]
	v_mfma_f32_16x16x32_bf16 v[44:47], v[142:145], v[182:185], v[44:47]
	v_mfma_f32_16x16x32_bf16 v[40:43], v[150:153], v[182:185], v[40:43]
	v_mfma_f32_16x16x32_bf16 v[28:31], v[142:145], v[194:197], v[28:31]
	v_mfma_f32_16x16x32_bf16 v[24:27], v[150:153], v[194:197], v[24:27]
	v_mfma_f32_16x16x32_bf16 v[12:15], v[142:145], v[214:217], v[12:15]
	v_mfma_f32_16x16x32_bf16 v[8:11], v[150:153], v[214:217], v[8:11]
	v_mfma_f32_16x16x32_bf16 v[52:55], v[154:157], v[170:173], v[52:55]
	v_mfma_f32_16x16x32_bf16 v[48:51], v[162:165], v[170:173], v[48:51]
	v_mfma_f32_16x16x32_bf16 v[36:39], v[154:157], v[178:181], v[36:39]
	v_mfma_f32_16x16x32_bf16 v[32:35], v[162:165], v[178:181], v[32:35]
	v_mfma_f32_16x16x32_bf16 v[20:23], v[154:157], v[190:193], v[20:23]
	v_mfma_f32_16x16x32_bf16 v[16:19], v[162:165], v[190:193], v[16:19]
	v_mfma_f32_16x16x32_bf16 v[4:7], v[154:157], v[198:201], v[4:7]
	v_mfma_f32_16x16x32_bf16 v[0:3], v[162:165], v[198:201], v[0:3]
	v_mfma_f32_16x16x32_bf16 v[52:55], v[158:161], v[174:177], v[52:55]
	v_mfma_f32_16x16x32_bf16 v[48:51], v[166:169], v[174:177], v[48:51]
	v_mfma_f32_16x16x32_bf16 v[36:39], v[158:161], v[182:185], v[36:39]
	v_mfma_f32_16x16x32_bf16 v[32:35], v[166:169], v[182:185], v[32:35]
	v_mfma_f32_16x16x32_bf16 v[20:23], v[158:161], v[194:197], v[20:23]
	v_mfma_f32_16x16x32_bf16 v[16:19], v[166:169], v[194:197], v[16:19]
	v_mfma_f32_16x16x32_bf16 v[4:7], v[158:161], v[214:217], v[4:7]
	v_mfma_f32_16x16x32_bf16 v[0:3], v[166:169], v[214:217], v[0:3]
	s_setprio 0
	s_barrier
	s_add_i32 s70, 0, 0x18000
	v_add_u32_e32 v64, s70, v136
	s_add_i32 s71, 0, 0x1c000
	ds_read_b128 v[138:141], v64
	ds_read_b128 v[142:145], v64 offset:1024
	ds_read_b128 v[146:149], v64 offset:2048
	ds_read_b128 v[150:153], v64 offset:3072
	v_add_u32_e32 v64, s71, v136
	ds_read_b128 v[154:157], v64
	ds_read_b128 v[158:161], v64 offset:1024
	ds_read_b128 v[162:165], v64 offset:2048
	ds_read_b128 v[166:169], v64 offset:3072
	s_add_u32 s60, s2, 0x40000
	v_mov_b32_e32 v64, v132
	s_mov_b32 m0, s52
	ds_read_b128 v[170:173], v137 offset:32768
	ds_read_b128 v[174:177], v137 offset:33792
	ds_read_b128 v[178:181], v137 offset:34816
	ds_read_b128 v[182:185], v137 offset:35840
	ds_read_b128 v[190:193], v137 offset:36864
	ds_read_b128 v[194:197], v137 offset:37888
	ds_read_b128 v[198:201], v137 offset:38912
	ds_read_b128 v[214:217], v137 offset:39936
	s_addc_u32 s61, s3, 0
	s_nop 0
	global_load_lds_dwordx4 v64, s[60:61]
	v_mov_b32_e32 v64, v134
	s_mov_b32 m0, s53
	s_nop 0
	global_load_lds_dwordx4 v64, s[60:61]
	s_waitcnt vmcnt(8)
	s_waitcnt lgkmcnt(0)
	s_barrier
	s_setprio 1
	s_waitcnt lgkmcnt(0)
	v_mfma_f32_16x16x32_bf16 v[126:129], v[138:141], v[170:173], v[126:129]
	v_mfma_f32_16x16x32_bf16 v[122:125], v[146:149], v[170:173], v[122:125]
	v_mfma_f32_16x16x32_bf16 v[110:113], v[138:141], v[178:181], v[110:113]
	v_mfma_f32_16x16x32_bf16 v[106:109], v[146:149], v[178:181], v[106:109]
	v_mfma_f32_16x16x32_bf16 v[94:97], v[138:141], v[190:193], v[94:97]
	v_mfma_f32_16x16x32_bf16 v[90:93], v[146:149], v[190:193], v[90:93]
	v_mfma_f32_16x16x32_bf16 v[78:81], v[138:141], v[198:201], v[78:81]
	v_mfma_f32_16x16x32_bf16 v[74:77], v[146:149], v[198:201], v[74:77]
	v_mfma_f32_16x16x32_bf16 v[126:129], v[142:145], v[174:177], v[126:129]
	v_mfma_f32_16x16x32_bf16 v[122:125], v[150:153], v[174:177], v[122:125]
	v_mfma_f32_16x16x32_bf16 v[110:113], v[142:145], v[182:185], v[110:113]
	v_mfma_f32_16x16x32_bf16 v[106:109], v[150:153], v[182:185], v[106:109]
	v_mfma_f32_16x16x32_bf16 v[94:97], v[142:145], v[194:197], v[94:97]
	v_mfma_f32_16x16x32_bf16 v[90:93], v[150:153], v[194:197], v[90:93]
	v_mfma_f32_16x16x32_bf16 v[78:81], v[142:145], v[214:217], v[78:81]
	v_mfma_f32_16x16x32_bf16 v[74:77], v[150:153], v[214:217], v[74:77]
	v_mfma_f32_16x16x32_bf16 v[118:121], v[154:157], v[170:173], v[118:121]
	v_mfma_f32_16x16x32_bf16 v[114:117], v[162:165], v[170:173], v[114:117]
	v_mfma_f32_16x16x32_bf16 v[102:105], v[154:157], v[178:181], v[102:105]
	v_mfma_f32_16x16x32_bf16 v[98:101], v[162:165], v[178:181], v[98:101]
	v_mfma_f32_16x16x32_bf16 v[86:89], v[154:157], v[190:193], v[86:89]
	v_mfma_f32_16x16x32_bf16 v[82:85], v[162:165], v[190:193], v[82:85]
	v_mfma_f32_16x16x32_bf16 v[70:73], v[154:157], v[198:201], v[70:73]
	v_mfma_f32_16x16x32_bf16 v[66:69], v[162:165], v[198:201], v[66:69]
	v_mfma_f32_16x16x32_bf16 v[118:121], v[158:161], v[174:177], v[118:121]
	v_mfma_f32_16x16x32_bf16 v[114:117], v[166:169], v[174:177], v[114:117]
	v_mfma_f32_16x16x32_bf16 v[102:105], v[158:161], v[182:185], v[102:105]
	v_mfma_f32_16x16x32_bf16 v[98:101], v[166:169], v[182:185], v[98:101]
	v_mfma_f32_16x16x32_bf16 v[86:89], v[158:161], v[194:197], v[86:89]
	v_mfma_f32_16x16x32_bf16 v[82:85], v[166:169], v[194:197], v[82:85]
	v_mfma_f32_16x16x32_bf16 v[70:73], v[158:161], v[214:217], v[70:73]
	v_mfma_f32_16x16x32_bf16 v[66:69], v[166:169], v[214:217], v[66:69]
	s_setprio 0
	s_barrier
	v_mov_b32_e32 v64, v133
	ds_read_b128 v[170:173], v137 offset:49152
	ds_read_b128 v[174:177], v137 offset:50176
	ds_read_b128 v[178:181], v137 offset:51200
	ds_read_b128 v[182:185], v137 offset:52224
	ds_read_b128 v[190:193], v137 offset:53248
	ds_read_b128 v[194:197], v137 offset:54272
	ds_read_b128 v[198:201], v137 offset:55296
	ds_read_b128 v[214:217], v137 offset:56320
	s_add_i32 s60, s70, s49
	v_lshl_add_u64 v[130:131], s[54:55], 0, v[64:65]
	v_lshl_add_u64 v[130:131], v[130:131], 0, s[24:25]
	s_mov_b32 m0, s60
	v_mov_b32_e32 v64, v135
	global_load_lds_dwordx4 v[130:131], off
	s_add_i32 m0, s60, 0x2000
	s_nop 0
	v_lshl_add_u64 v[130:131], s[54:55], 0, v[64:65]
	s_add_u32 s54, s54, 0x40080
	v_lshl_add_u64 v[130:131], v[130:131], 0, s[24:25]
	s_addc_u32 s55, s55, 0
	v_mov_b32_e32 v64, v133
	s_add_i32 s60, s71, s49
	global_load_lds_dwordx4 v[130:131], off
	s_mov_b32 m0, s60
	s_nop 0
	global_load_lds_dwordx4 v64, s[54:55]
	v_mov_b32_e32 v64, v135
	s_add_i32 m0, s60, 0x2000
	s_nop 0
	global_load_lds_dwordx4 v64, s[54:55]
	v_mov_b32_e32 v64, v132
	s_mov_b32 m0, s22
	v_lshl_add_u64 v[130:131], s[2:3], 0, v[64:65]
	v_lshl_add_u64 v[130:131], v[130:131], 0, s[24:25]
	v_mov_b32_e32 v64, v134
	global_load_lds_dwordx4 v[130:131], off
	s_mov_b32 m0, s56
	v_lshl_add_u64 v[130:131], s[2:3], 0, v[64:65]
	v_lshl_add_u64 v[130:131], v[130:131], 0, s[24:25]
	global_load_lds_dwordx4 v[130:131], off
	s_waitcnt vmcnt(8)
	s_waitcnt lgkmcnt(0)
	s_barrier
	s_setprio 1
	s_waitcnt lgkmcnt(0)
	v_mfma_f32_16x16x32_bf16 v[60:63], v[138:141], v[170:173], v[60:63]
	v_mfma_f32_16x16x32_bf16 v[56:59], v[146:149], v[170:173], v[56:59]
	v_mfma_f32_16x16x32_bf16 v[44:47], v[138:141], v[178:181], v[44:47]
	v_mfma_f32_16x16x32_bf16 v[40:43], v[146:149], v[178:181], v[40:43]
	v_mfma_f32_16x16x32_bf16 v[28:31], v[138:141], v[190:193], v[28:31]
	v_mfma_f32_16x16x32_bf16 v[24:27], v[146:149], v[190:193], v[24:27]
	v_mfma_f32_16x16x32_bf16 v[12:15], v[138:141], v[198:201], v[12:15]
	v_mfma_f32_16x16x32_bf16 v[8:11], v[146:149], v[198:201], v[8:11]
	v_mfma_f32_16x16x32_bf16 v[60:63], v[142:145], v[174:177], v[60:63]
	v_mfma_f32_16x16x32_bf16 v[56:59], v[150:153], v[174:177], v[56:59]
	v_mfma_f32_16x16x32_bf16 v[44:47], v[142:145], v[182:185], v[44:47]
	v_mfma_f32_16x16x32_bf16 v[40:43], v[150:153], v[182:185], v[40:43]
	v_mfma_f32_16x16x32_bf16 v[28:31], v[142:145], v[194:197], v[28:31]
	v_mfma_f32_16x16x32_bf16 v[24:27], v[150:153], v[194:197], v[24:27]
	v_mfma_f32_16x16x32_bf16 v[12:15], v[142:145], v[214:217], v[12:15]
	v_mfma_f32_16x16x32_bf16 v[8:11], v[150:153], v[214:217], v[8:11]
	v_mfma_f32_16x16x32_bf16 v[52:55], v[154:157], v[170:173], v[52:55]
	v_mfma_f32_16x16x32_bf16 v[48:51], v[162:165], v[170:173], v[48:51]
	v_mfma_f32_16x16x32_bf16 v[36:39], v[154:157], v[178:181], v[36:39]
	v_mfma_f32_16x16x32_bf16 v[32:35], v[162:165], v[178:181], v[32:35]
	v_mfma_f32_16x16x32_bf16 v[20:23], v[154:157], v[190:193], v[20:23]
	v_mfma_f32_16x16x32_bf16 v[16:19], v[162:165], v[190:193], v[16:19]
	v_mfma_f32_16x16x32_bf16 v[4:7], v[154:157], v[198:201], v[4:7]
	v_mfma_f32_16x16x32_bf16 v[0:3], v[162:165], v[198:201], v[0:3]
	v_mfma_f32_16x16x32_bf16 v[52:55], v[158:161], v[174:177], v[52:55]
	v_mfma_f32_16x16x32_bf16 v[48:51], v[166:169], v[174:177], v[48:51]
	v_mfma_f32_16x16x32_bf16 v[36:39], v[158:161], v[182:185], v[36:39]
	v_mfma_f32_16x16x32_bf16 v[32:35], v[166:169], v[182:185], v[32:35]
	v_mfma_f32_16x16x32_bf16 v[20:23], v[158:161], v[194:197], v[20:23]
	v_mfma_f32_16x16x32_bf16 v[16:19], v[166:169], v[194:197], v[16:19]
	v_mfma_f32_16x16x32_bf16 v[4:7], v[158:161], v[214:217], v[4:7]
	v_mfma_f32_16x16x32_bf16 v[0:3], v[166:169], v[214:217], v[0:3]
	s_setprio 0
	s_barrier
	s_add_i32 s69, s69, 2
	s_add_u32 s94, s94, 0x100
	s_addc_u32 s95, s95, 0
	s_add_u32 s67, s67, 0x100
	s_addc_u32 s68, s68, 0
	s_cmp_gt_u32 s69, 13
	s_cbranch_scc0 .LBB0_80
	s_and_b64 vcc, exec, s[80:81]
	s_cbranch_vccz .LBB0_83
	s_barrier

.LBB0_95:
	s_add_i32 s58, 0, 0x10000
	s_add_i32 s59, 0, 0x14000
	v_add_u32_e32 v64, s58, v134
	ds_read_b128 v[136:139], v64
	ds_read_b128 v[140:143], v64 offset:1024
	ds_read_b128 v[144:147], v64 offset:2048
	ds_read_b128 v[148:151], v64 offset:3072
	v_add_u32_e32 v64, s59, v134
	ds_read_b128 v[152:155], v64
	ds_read_b128 v[156:159], v64 offset:1024
	ds_read_b128 v[160:163], v64 offset:2048
	ds_read_b128 v[164:167], v64 offset:3072
	s_add_u32 s2, s84, 0xf7ac0080
	s_addc_u32 s3, s85, -1
	s_cmp_lg_u32 s53, 12
	s_cselect_b32 s54, s2, 0
	s_cselect_b32 s55, s3, 0
	s_add_u32 s2, s82, s54
	s_addc_u32 s3, s83, s55
	s_add_u32 s54, s46, s54
	s_addc_u32 s55, s47, s55
	s_add_i32 m0, s10, 0xc000
	v_mov_b32_e32 v64, v130
	s_add_u32 s56, s51, s84
	ds_read_b128 v[168:171], v135
	ds_read_b128 v[172:175], v135 offset:1024
	ds_read_b128 v[176:179], v135 offset:2048
	ds_read_b128 v[180:183], v135 offset:3072
	ds_read_b128 v[184:187], v135 offset:4096
	ds_read_b128 v[190:193], v135 offset:5120
	ds_read_b128 v[194:197], v135 offset:6144
	ds_read_b128 v[198:201], v135 offset:7168
	s_addc_u32 s57, s52, s85
	global_load_lds_dwordx4 v64, s[56:57]
	v_mov_b32_e32 v64, v132
	s_add_i32 m0, s10, 0xe000
	s_nop 0
	global_load_lds_dwordx4 v64, s[56:57]
	s_waitcnt vmcnt(8)
	s_waitcnt lgkmcnt(0)
	s_barrier
	s_setprio 1
	s_waitcnt lgkmcnt(0)
	v_mfma_f32_16x16x32_bf16 v[52:55], v[136:139], v[168:171], v[52:55]
	v_mfma_f32_16x16x32_bf16 v[48:51], v[144:147], v[168:171], v[48:51]
	v_mfma_f32_16x16x32_bf16 v[4:7], v[136:139], v[176:179], v[4:7]
	v_mfma_f32_16x16x32_bf16 v[0:3], v[144:147], v[176:179], v[0:3]
	v_mfma_f32_16x16x32_bf16 v[36:39], v[136:139], v[184:187], v[36:39]
	v_mfma_f32_16x16x32_bf16 v[32:35], v[144:147], v[184:187], v[32:35]
	v_mfma_f32_16x16x32_bf16 v[78:81], v[136:139], v[194:197], v[78:81]
	v_mfma_f32_16x16x32_bf16 v[74:77], v[144:147], v[194:197], v[74:77]
	v_mfma_f32_16x16x32_bf16 v[52:55], v[140:143], v[172:175], v[52:55]
	v_mfma_f32_16x16x32_bf16 v[48:51], v[148:151], v[172:175], v[48:51]
	v_mfma_f32_16x16x32_bf16 v[4:7], v[140:143], v[180:183], v[4:7]
	v_mfma_f32_16x16x32_bf16 v[0:3], v[148:151], v[180:183], v[0:3]
	v_mfma_f32_16x16x32_bf16 v[36:39], v[140:143], v[190:193], v[36:39]
	v_mfma_f32_16x16x32_bf16 v[32:35], v[148:151], v[190:193], v[32:35]
	v_mfma_f32_16x16x32_bf16 v[78:81], v[140:143], v[198:201], v[78:81]
	v_mfma_f32_16x16x32_bf16 v[74:77], v[148:151], v[198:201], v[74:77]
	v_mfma_f32_16x16x32_bf16 v[24:27], v[152:155], v[168:171], v[24:27]
	v_mfma_f32_16x16x32_bf16 v[20:23], v[160:163], v[168:171], v[20:23]
	v_mfma_f32_16x16x32_bf16 v[12:15], v[152:155], v[176:179], v[12:15]
	v_mfma_f32_16x16x32_bf16 v[28:31], v[160:163], v[176:179], v[28:31]
	v_mfma_f32_16x16x32_bf16 v[56:59], v[152:155], v[184:187], v[56:59]
	v_mfma_f32_16x16x32_bf16 v[66:69], v[160:163], v[184:187], v[66:69]
	v_mfma_f32_16x16x32_bf16 v[86:89], v[152:155], v[194:197], v[86:89]
	v_mfma_f32_16x16x32_bf16 v[94:97], v[160:163], v[194:197], v[94:97]
	v_mfma_f32_16x16x32_bf16 v[24:27], v[156:159], v[172:175], v[24:27]
	v_mfma_f32_16x16x32_bf16 v[20:23], v[164:167], v[172:175], v[20:23]
	v_mfma_f32_16x16x32_bf16 v[12:15], v[156:159], v[180:183], v[12:15]
	v_mfma_f32_16x16x32_bf16 v[28:31], v[164:167], v[180:183], v[28:31]
	v_mfma_f32_16x16x32_bf16 v[56:59], v[156:159], v[190:193], v[56:59]
	v_mfma_f32_16x16x32_bf16 v[66:69], v[164:167], v[190:193], v[66:69]
	v_mfma_f32_16x16x32_bf16 v[86:89], v[156:159], v[198:201], v[86:89]
	v_mfma_f32_16x16x32_bf16 v[94:97], v[164:167], v[198:201], v[94:97]
	s_setprio 0
	s_barrier
	v_mov_b32_e32 v64, v131
	s_add_i32 s56, s58, s7
	ds_read_b128 v[168:171], v135 offset:16384
	ds_read_b128 v[172:175], v135 offset:17408
	ds_read_b128 v[176:179], v135 offset:18432
	ds_read_b128 v[180:183], v135 offset:19456
	ds_read_b128 v[184:187], v135 offset:20480
	ds_read_b128 v[190:193], v135 offset:21504
	ds_read_b128 v[194:197], v135 offset:22528
	ds_read_b128 v[198:201], v135 offset:23552
	s_mov_b32 m0, s56
	s_nop 0
	global_load_lds_dwordx4 v64, s[54:55]
	v_mov_b32_e32 v64, v133
	s_add_i32 m0, s56, 0x2000
	s_add_u32 s56, s54, 0x40000
	global_load_lds_dwordx4 v64, s[54:55]
	s_addc_u32 s57, s55, 0
	v_mov_b32_e32 v64, v131
	s_add_i32 s58, s59, s7
	s_mov_b32 m0, s58
	s_nop 0
	global_load_lds_dwordx4 v64, s[56:57]
	v_mov_b32_e32 v64, v133
	s_add_i32 m0, s58, 0x2000
	s_nop 0
	global_load_lds_dwordx4 v64, s[56:57]
	v_mov_b32_e32 v64, v130
	s_mov_b32 m0, s10
	s_nop 0
	global_load_lds_dwordx4 v64, s[2:3]
	v_mov_b32_e32 v64, v132
	s_mov_b32 m0, s17
	s_nop 0
	global_load_lds_dwordx4 v64, s[2:3]
	s_waitcnt vmcnt(8)
	s_waitcnt lgkmcnt(0)
	s_barrier
	s_setprio 1
	s_waitcnt lgkmcnt(0)
	v_mfma_f32_16x16x32_bf16 v[106:109], v[136:139], v[168:171], v[106:109]
	v_mfma_f32_16x16x32_bf16 v[102:105], v[144:147], v[168:171], v[102:105]
	v_mfma_f32_16x16x32_bf16 v[126:129], v[136:139], v[176:179], v[126:129]
	v_mfma_f32_16x16x32_bf16 v[122:125], v[144:147], v[176:179], v[122:125]
	v_mfma_f32_16x16x32_bf16 v[90:93], v[136:139], v[184:187], v[90:93]
	v_mfma_f32_16x16x32_bf16 v[82:85], v[144:147], v[184:187], v[82:85]
	v_mfma_f32_16x16x32_bf16 v[44:47], v[136:139], v[194:197], v[44:47]
	v_mfma_f32_16x16x32_bf16 v[40:43], v[144:147], v[194:197], v[40:43]
	v_mfma_f32_16x16x32_bf16 v[106:109], v[140:143], v[172:175], v[106:109]
	v_mfma_f32_16x16x32_bf16 v[102:105], v[148:151], v[172:175], v[102:105]
	v_mfma_f32_16x16x32_bf16 v[126:129], v[140:143], v[180:183], v[126:129]
	v_mfma_f32_16x16x32_bf16 v[122:125], v[148:151], v[180:183], v[122:125]
	v_mfma_f32_16x16x32_bf16 v[90:93], v[140:143], v[190:193], v[90:93]
	v_mfma_f32_16x16x32_bf16 v[82:85], v[148:151], v[190:193], v[82:85]
	v_mfma_f32_16x16x32_bf16 v[44:47], v[140:143], v[198:201], v[44:47]
	v_mfma_f32_16x16x32_bf16 v[40:43], v[148:151], v[198:201], v[40:43]
	v_mfma_f32_16x16x32_bf16 v[114:117], v[152:155], v[168:171], v[114:117]
	v_mfma_f32_16x16x32_bf16 v[118:121], v[160:163], v[168:171], v[118:121]
	v_mfma_f32_16x16x32_bf16 v[110:113], v[152:155], v[176:179], v[110:113]
	v_mfma_f32_16x16x32_bf16 v[98:101], v[160:163], v[176:179], v[98:101]
	v_mfma_f32_16x16x32_bf16 v[70:73], v[152:155], v[184:187], v[70:73]
	v_mfma_f32_16x16x32_bf16 v[60:63], v[160:163], v[184:187], v[60:63]
	v_mfma_f32_16x16x32_bf16 v[16:19], v[152:155], v[194:197], v[16:19]
	v_mfma_f32_16x16x32_bf16 v[8:11], v[160:163], v[194:197], v[8:11]
	v_mfma_f32_16x16x32_bf16 v[114:117], v[156:159], v[172:175], v[114:117]
	v_mfma_f32_16x16x32_bf16 v[118:121], v[164:167], v[172:175], v[118:121]
	v_mfma_f32_16x16x32_bf16 v[110:113], v[156:159], v[180:183], v[110:113]
	v_mfma_f32_16x16x32_bf16 v[98:101], v[164:167], v[180:183], v[98:101]
	v_mfma_f32_16x16x32_bf16 v[70:73], v[156:159], v[190:193], v[70:73]
	v_mfma_f32_16x16x32_bf16 v[60:63], v[164:167], v[190:193], v[60:63]
	v_mfma_f32_16x16x32_bf16 v[16:19], v[156:159], v[198:201], v[16:19]
	v_mfma_f32_16x16x32_bf16 v[8:11], v[164:167], v[198:201], v[8:11]
	s_setprio 0
	s_barrier
	s_add_i32 s58, 0, 0x18000
	v_add_u32_e32 v64, s58, v134
	s_add_i32 s59, 0, 0x1c000
	ds_read_b128 v[136:139], v64
	ds_read_b128 v[140:143], v64 offset:1024
	ds_read_b128 v[144:147], v64 offset:2048
	ds_read_b128 v[148:151], v64 offset:3072
	v_add_u32_e32 v64, s59, v134
	ds_read_b128 v[152:155], v64
	ds_read_b128 v[156:159], v64 offset:1024
	ds_read_b128 v[160:163], v64 offset:2048
	ds_read_b128 v[164:167], v64 offset:3072
	s_add_u32 s56, s2, 0x40000
	v_mov_b32_e32 v64, v130
	s_mov_b32 m0, s22
	ds_read_b128 v[168:171], v135 offset:32768
	ds_read_b128 v[172:175], v135 offset:33792
	ds_read_b128 v[176:179], v135 offset:34816
	ds_read_b128 v[180:183], v135 offset:35840
	ds_read_b128 v[184:187], v135 offset:36864
	ds_read_b128 v[190:193], v135 offset:37888
	ds_read_b128 v[194:197], v135 offset:38912
	ds_read_b128 v[198:201], v135 offset:39936
	s_addc_u32 s57, s3, 0
	s_nop 0
	global_load_lds_dwordx4 v64, s[56:57]
	v_mov_b32_e32 v64, v132
	s_mov_b32 m0, s41
	s_nop 0
	global_load_lds_dwordx4 v64, s[56:57]
	s_waitcnt vmcnt(8)
	s_waitcnt lgkmcnt(0)
	s_barrier
	s_setprio 1
	s_waitcnt lgkmcnt(0)
	v_mfma_f32_16x16x32_bf16 v[52:55], v[136:139], v[168:171], v[52:55]
	v_mfma_f32_16x16x32_bf16 v[48:51], v[144:147], v[168:171], v[48:51]
	v_mfma_f32_16x16x32_bf16 v[4:7], v[136:139], v[176:179], v[4:7]
	v_mfma_f32_16x16x32_bf16 v[0:3], v[144:147], v[176:179], v[0:3]
	v_mfma_f32_16x16x32_bf16 v[36:39], v[136:139], v[184:187], v[36:39]
	v_mfma_f32_16x16x32_bf16 v[32:35], v[144:147], v[184:187], v[32:35]
	v_mfma_f32_16x16x32_bf16 v[78:81], v[136:139], v[194:197], v[78:81]
	v_mfma_f32_16x16x32_bf16 v[74:77], v[144:147], v[194:197], v[74:77]
	v_mfma_f32_16x16x32_bf16 v[52:55], v[140:143], v[172:175], v[52:55]
	v_mfma_f32_16x16x32_bf16 v[48:51], v[148:151], v[172:175], v[48:51]
	v_mfma_f32_16x16x32_bf16 v[4:7], v[140:143], v[180:183], v[4:7]
	v_mfma_f32_16x16x32_bf16 v[0:3], v[148:151], v[180:183], v[0:3]
	v_mfma_f32_16x16x32_bf16 v[36:39], v[140:143], v[190:193], v[36:39]
	v_mfma_f32_16x16x32_bf16 v[32:35], v[148:151], v[190:193], v[32:35]
	v_mfma_f32_16x16x32_bf16 v[78:81], v[140:143], v[198:201], v[78:81]
	v_mfma_f32_16x16x32_bf16 v[74:77], v[148:151], v[198:201], v[74:77]
	v_mfma_f32_16x16x32_bf16 v[24:27], v[152:155], v[168:171], v[24:27]
	v_mfma_f32_16x16x32_bf16 v[20:23], v[160:163], v[168:171], v[20:23]
	v_mfma_f32_16x16x32_bf16 v[12:15], v[152:155], v[176:179], v[12:15]
	v_mfma_f32_16x16x32_bf16 v[28:31], v[160:163], v[176:179], v[28:31]
	v_mfma_f32_16x16x32_bf16 v[56:59], v[152:155], v[184:187], v[56:59]
	v_mfma_f32_16x16x32_bf16 v[66:69], v[160:163], v[184:187], v[66:69]
	v_mfma_f32_16x16x32_bf16 v[86:89], v[152:155], v[194:197], v[86:89]
	v_mfma_f32_16x16x32_bf16 v[94:97], v[160:163], v[194:197], v[94:97]
	v_mfma_f32_16x16x32_bf16 v[24:27], v[156:159], v[172:175], v[24:27]
	v_mfma_f32_16x16x32_bf16 v[20:23], v[164:167], v[172:175], v[20:23]
	v_mfma_f32_16x16x32_bf16 v[12:15], v[156:159], v[180:183], v[12:15]
	v_mfma_f32_16x16x32_bf16 v[28:31], v[164:167], v[180:183], v[28:31]
	v_mfma_f32_16x16x32_bf16 v[56:59], v[156:159], v[190:193], v[56:59]
	v_mfma_f32_16x16x32_bf16 v[66:69], v[164:167], v[190:193], v[66:69]
	v_mfma_f32_16x16x32_bf16 v[86:89], v[156:159], v[198:201], v[86:89]
	v_mfma_f32_16x16x32_bf16 v[94:97], v[164:167], v[198:201], v[94:97]
	s_setprio 0
	s_barrier
	v_mov_b32_e32 v64, v131
	ds_read_b128 v[168:171], v135 offset:49152
	ds_read_b128 v[172:175], v135 offset:50176
	ds_read_b128 v[176:179], v135 offset:51200
	ds_read_b128 v[180:183], v135 offset:52224
	ds_read_b128 v[184:187], v135 offset:53248
	ds_read_b128 v[190:193], v135 offset:54272
	ds_read_b128 v[194:197], v135 offset:55296
	ds_read_b128 v[198:201], v135 offset:56320
	s_add_i32 s56, s58, s7
	v_lshl_add_u64 v[214:215], s[54:55], 0, v[64:65]
	v_lshl_add_u64 v[214:215], v[214:215], 0, s[24:25]
	s_mov_b32 m0, s56
	v_mov_b32_e32 v64, v133
	global_load_lds_dwordx4 v[214:215], off
	s_add_i32 m0, s56, 0x2000
	s_nop 0
	v_lshl_add_u64 v[214:215], s[54:55], 0, v[64:65]
	s_add_u32 s54, s54, 0x40080
	v_lshl_add_u64 v[214:215], v[214:215], 0, s[24:25]
	s_addc_u32 s55, s55, 0
	v_mov_b32_e32 v64, v131
	s_add_i32 s56, s59, s7
	global_load_lds_dwordx4 v[214:215], off
	s_mov_b32 m0, s56
	s_nop 0
	global_load_lds_dwordx4 v64, s[54:55]
	v_mov_b32_e32 v64, v133
	s_add_i32 m0, s56, 0x2000
	s_nop 0
	global_load_lds_dwordx4 v64, s[54:55]
	v_mov_b32_e32 v64, v130
	s_mov_b32 m0, s49
	v_lshl_add_u64 v[214:215], s[2:3], 0, v[64:65]
	v_lshl_add_u64 v[214:215], v[214:215], 0, s[24:25]
	v_mov_b32_e32 v64, v132
	global_load_lds_dwordx4 v[214:215], off
	s_mov_b32 m0, s50
	v_lshl_add_u64 v[214:215], s[2:3], 0, v[64:65]
	v_lshl_add_u64 v[214:215], v[214:215], 0, s[24:25]
	global_load_lds_dwordx4 v[214:215], off
	s_waitcnt vmcnt(8)
	s_waitcnt lgkmcnt(0)
	s_barrier
	s_setprio 1
	s_waitcnt lgkmcnt(0)
	v_mfma_f32_16x16x32_bf16 v[106:109], v[136:139], v[168:171], v[106:109]
	v_mfma_f32_16x16x32_bf16 v[102:105], v[144:147], v[168:171], v[102:105]
	v_mfma_f32_16x16x32_bf16 v[126:129], v[136:139], v[176:179], v[126:129]
	v_mfma_f32_16x16x32_bf16 v[122:125], v[144:147], v[176:179], v[122:125]
	v_mfma_f32_16x16x32_bf16 v[90:93], v[136:139], v[184:187], v[90:93]
	v_mfma_f32_16x16x32_bf16 v[82:85], v[144:147], v[184:187], v[82:85]
	v_mfma_f32_16x16x32_bf16 v[44:47], v[136:139], v[194:197], v[44:47]
	v_mfma_f32_16x16x32_bf16 v[40:43], v[144:147], v[194:197], v[40:43]
	v_mfma_f32_16x16x32_bf16 v[106:109], v[140:143], v[172:175], v[106:109]
	v_mfma_f32_16x16x32_bf16 v[102:105], v[148:151], v[172:175], v[102:105]
	v_mfma_f32_16x16x32_bf16 v[126:129], v[140:143], v[180:183], v[126:129]
	v_mfma_f32_16x16x32_bf16 v[122:125], v[148:151], v[180:183], v[122:125]
	v_mfma_f32_16x16x32_bf16 v[90:93], v[140:143], v[190:193], v[90:93]
	v_mfma_f32_16x16x32_bf16 v[82:85], v[148:151], v[190:193], v[82:85]
	v_mfma_f32_16x16x32_bf16 v[44:47], v[140:143], v[198:201], v[44:47]
	v_mfma_f32_16x16x32_bf16 v[40:43], v[148:151], v[198:201], v[40:43]
	v_mfma_f32_16x16x32_bf16 v[114:117], v[152:155], v[168:171], v[114:117]
	v_mfma_f32_16x16x32_bf16 v[118:121], v[160:163], v[168:171], v[118:121]
	v_mfma_f32_16x16x32_bf16 v[110:113], v[152:155], v[176:179], v[110:113]
	v_mfma_f32_16x16x32_bf16 v[98:101], v[160:163], v[176:179], v[98:101]
	v_mfma_f32_16x16x32_bf16 v[70:73], v[152:155], v[184:187], v[70:73]
	v_mfma_f32_16x16x32_bf16 v[60:63], v[160:163], v[184:187], v[60:63]
	v_mfma_f32_16x16x32_bf16 v[16:19], v[152:155], v[194:197], v[16:19]
	v_mfma_f32_16x16x32_bf16 v[8:11], v[160:163], v[194:197], v[8:11]
	v_mfma_f32_16x16x32_bf16 v[114:117], v[156:159], v[172:175], v[114:117]
	v_mfma_f32_16x16x32_bf16 v[118:121], v[164:167], v[172:175], v[118:121]
	v_mfma_f32_16x16x32_bf16 v[110:113], v[156:159], v[180:183], v[110:113]
	v_mfma_f32_16x16x32_bf16 v[98:101], v[164:167], v[180:183], v[98:101]
	v_mfma_f32_16x16x32_bf16 v[70:73], v[156:159], v[190:193], v[70:73]
	v_mfma_f32_16x16x32_bf16 v[60:63], v[164:167], v[190:193], v[60:63]
	v_mfma_f32_16x16x32_bf16 v[16:19], v[156:159], v[198:201], v[16:19]
	v_mfma_f32_16x16x32_bf16 v[8:11], v[164:167], v[198:201], v[8:11]
	s_setprio 0
	s_barrier
	s_add_i32 s53, s53, 2
	s_add_u32 s84, s84, 0x100
	s_addc_u32 s85, s85, 0
	s_cmp_gt_u32 s53, 13
	s_cbranch_scc0 .LBB0_95
	s_cmp_lt_u32 s48, 4
	s_cbranch_scc0 .LBB0_98
	s_barrier

.LBB0_145:
	s_add_i32 s87, 0, 0x10000
	s_add_i32 s85, 0, 0x14000
	v_add_u32_e32 v64, s87, v196
	ds_read_b128 v[132:135], v64
	ds_read_b128 v[136:139], v64 offset:1024
	ds_read_b128 v[140:143], v64 offset:2048
	ds_read_b128 v[144:147], v64 offset:3072
	v_add_u32_e32 v64, s85, v196
	ds_read_b128 v[148:151], v64
	ds_read_b128 v[152:155], v64 offset:1024
	ds_read_b128 v[156:159], v64 offset:2048
	ds_read_b128 v[160:163], v64 offset:3072
	s_add_i32 s77, s77, 2
	s_cmp_gt_u32 s77, 5
	s_cselect_b32 s2, 0xffc00, 0
	s_add_u32 s60, s92, s94
	s_addc_u32 s61, s93, s95
	s_add_u32 s54, s60, 0x100
	s_addc_u32 s3, s61, 0
	s_add_u32 s2, s2, s94
	s_addc_u32 s55, 0, s95
	s_add_u32 s85, s71, s2
	s_addc_u32 s55, s76, s55
	s_cmpk_eq_i32 s94, 0x700
	s_cselect_b32 s3, s64, s3
	s_cselect_b32 s2, s65, s54
	s_cselect_b32 s55, s68, s55
	s_cselect_b32 s54, s69, s85
	s_add_i32 s85, 0, 0x14000
	v_mov_b32_e32 v64, v192
	ds_read_b128 v[164:167], v197
	ds_read_b128 v[168:171], v197 offset:1024
	ds_read_b128 v[172:175], v197 offset:2048
	ds_read_b128 v[176:179], v197 offset:3072
	ds_read_b128 v[180:183], v197 offset:4096
	ds_read_b128 v[184:187], v197 offset:5120
	ds_read_b128 v[198:201], v197 offset:6144
	ds_read_b128 v[214:217], v197 offset:7168
	s_add_i32 m0, s50, 0xc000
	v_lshl_add_u64 v[66:67], s[60:61], 0, v[64:65]
	v_lshl_add_u64 v[66:67], v[66:67], 0, s[34:35]
	v_mov_b32_e32 v64, v194
	global_load_lds_dwordx4 v[66:67], off
	s_add_i32 m0, s50, 0xe000
	v_lshl_add_u64 v[66:67], s[60:61], 0, v[64:65]
	v_lshl_add_u64 v[66:67], v[66:67], 0, s[34:35]
	global_load_lds_dwordx4 v[66:67], off
	s_waitcnt vmcnt(8)
	s_waitcnt lgkmcnt(0)
	s_barrier
	s_setprio 1
	s_waitcnt lgkmcnt(0)
	v_mfma_f32_16x16x32_bf16 v[128:131], v[132:135], v[164:167], v[128:131]
	v_mfma_f32_16x16x32_bf16 v[124:127], v[140:143], v[164:167], v[124:127]
	v_mfma_f32_16x16x32_bf16 v[112:115], v[132:135], v[172:175], v[112:115]
	v_mfma_f32_16x16x32_bf16 v[108:111], v[140:143], v[172:175], v[108:111]
	v_mfma_f32_16x16x32_bf16 v[96:99], v[132:135], v[180:183], v[96:99]
	v_mfma_f32_16x16x32_bf16 v[92:95], v[140:143], v[180:183], v[92:95]
	v_mfma_f32_16x16x32_bf16 v[80:83], v[132:135], v[198:201], v[80:83]
	v_mfma_f32_16x16x32_bf16 v[76:79], v[140:143], v[198:201], v[76:79]
	v_mfma_f32_16x16x32_bf16 v[128:131], v[136:139], v[168:171], v[128:131]
	v_mfma_f32_16x16x32_bf16 v[124:127], v[144:147], v[168:171], v[124:127]
	v_mfma_f32_16x16x32_bf16 v[112:115], v[136:139], v[176:179], v[112:115]
	v_mfma_f32_16x16x32_bf16 v[108:111], v[144:147], v[176:179], v[108:111]
	v_mfma_f32_16x16x32_bf16 v[96:99], v[136:139], v[184:187], v[96:99]
	v_mfma_f32_16x16x32_bf16 v[92:95], v[144:147], v[184:187], v[92:95]
	v_mfma_f32_16x16x32_bf16 v[80:83], v[136:139], v[214:217], v[80:83]
	v_mfma_f32_16x16x32_bf16 v[76:79], v[144:147], v[214:217], v[76:79]
	v_mfma_f32_16x16x32_bf16 v[120:123], v[148:151], v[164:167], v[120:123]
	v_mfma_f32_16x16x32_bf16 v[116:119], v[156:159], v[164:167], v[116:119]
	v_mfma_f32_16x16x32_bf16 v[104:107], v[148:151], v[172:175], v[104:107]
	v_mfma_f32_16x16x32_bf16 v[100:103], v[156:159], v[172:175], v[100:103]
	v_mfma_f32_16x16x32_bf16 v[88:91], v[148:151], v[180:183], v[88:91]
	v_mfma_f32_16x16x32_bf16 v[84:87], v[156:159], v[180:183], v[84:87]
	v_mfma_f32_16x16x32_bf16 v[72:75], v[148:151], v[198:201], v[72:75]
	v_mfma_f32_16x16x32_bf16 v[66:69], v[156:159], v[198:201], v[68:71]
	v_mfma_f32_16x16x32_bf16 v[120:123], v[152:155], v[168:171], v[120:123]
	v_mfma_f32_16x16x32_bf16 v[116:119], v[160:163], v[168:171], v[116:119]
	v_mfma_f32_16x16x32_bf16 v[104:107], v[152:155], v[176:179], v[104:107]
	v_mfma_f32_16x16x32_bf16 v[100:103], v[160:163], v[176:179], v[100:103]
	v_mfma_f32_16x16x32_bf16 v[88:91], v[152:155], v[184:187], v[88:91]
	v_mfma_f32_16x16x32_bf16 v[84:87], v[160:163], v[184:187], v[84:87]
	v_mfma_f32_16x16x32_bf16 v[72:75], v[152:155], v[214:217], v[72:75]
	v_mfma_f32_16x16x32_bf16 v[66:69], v[160:163], v[214:217], v[66:69]
	s_setprio 0
	s_barrier
	v_mov_b32_e32 v64, v193
	s_add_i32 s60, s87, s49
	ds_read_b128 v[164:167], v197 offset:16384
	ds_read_b128 v[168:171], v197 offset:17408
	ds_read_b128 v[172:175], v197 offset:18432
	ds_read_b128 v[176:179], v197 offset:19456
	ds_read_b128 v[180:183], v197 offset:20480
	ds_read_b128 v[184:187], v197 offset:21504
	ds_read_b128 v[198:201], v197 offset:22528
	ds_read_b128 v[214:217], v197 offset:23552
	s_mov_b32 m0, s60
	s_nop 0
	global_load_lds_dwordx4 v64, s[54:55]
	v_mov_b32_e32 v64, v195
	s_add_i32 m0, s60, 0x2000
	s_add_u32 s60, s54, 0x20000
	global_load_lds_dwordx4 v64, s[54:55]
	s_addc_u32 s61, s55, 0
	v_mov_b32_e32 v64, v193
	s_add_i32 s85, s85, s49
	s_mov_b32 m0, s85
	s_nop 0
	global_load_lds_dwordx4 v64, s[60:61]
	v_mov_b32_e32 v64, v195
	s_add_i32 m0, s85, 0x2000
	s_nop 0
	global_load_lds_dwordx4 v64, s[60:61]
	v_mov_b32_e32 v64, v192
	s_mov_b32 m0, s50
	s_nop 0
	global_load_lds_dwordx4 v64, s[2:3]
	v_mov_b32_e32 v64, v194
	s_mov_b32 m0, s51
	s_nop 0
	global_load_lds_dwordx4 v64, s[2:3]
	s_waitcnt vmcnt(8)
	s_waitcnt lgkmcnt(0)
	s_barrier
	s_setprio 1
	s_waitcnt lgkmcnt(0)
	v_mfma_f32_16x16x32_bf16 v[60:63], v[132:135], v[164:167], v[60:63]
	v_mfma_f32_16x16x32_bf16 v[56:59], v[140:143], v[164:167], v[56:59]
	v_mfma_f32_16x16x32_bf16 v[44:47], v[132:135], v[172:175], v[44:47]
	v_mfma_f32_16x16x32_bf16 v[40:43], v[140:143], v[172:175], v[40:43]
	v_mfma_f32_16x16x32_bf16 v[28:31], v[132:135], v[180:183], v[28:31]
	v_mfma_f32_16x16x32_bf16 v[24:27], v[140:143], v[180:183], v[24:27]
	v_mfma_f32_16x16x32_bf16 v[12:15], v[132:135], v[198:201], v[12:15]
	v_mfma_f32_16x16x32_bf16 v[8:11], v[140:143], v[198:201], v[8:11]
	v_mfma_f32_16x16x32_bf16 v[60:63], v[136:139], v[168:171], v[60:63]
	v_mfma_f32_16x16x32_bf16 v[56:59], v[144:147], v[168:171], v[56:59]
	v_mfma_f32_16x16x32_bf16 v[44:47], v[136:139], v[176:179], v[44:47]
	v_mfma_f32_16x16x32_bf16 v[40:43], v[144:147], v[176:179], v[40:43]
	v_mfma_f32_16x16x32_bf16 v[28:31], v[136:139], v[184:187], v[28:31]
	v_mfma_f32_16x16x32_bf16 v[24:27], v[144:147], v[184:187], v[24:27]
	v_mfma_f32_16x16x32_bf16 v[12:15], v[136:139], v[214:217], v[12:15]
	v_mfma_f32_16x16x32_bf16 v[8:11], v[144:147], v[214:217], v[8:11]
	v_mfma_f32_16x16x32_bf16 v[52:55], v[148:151], v[164:167], v[52:55]
	v_mfma_f32_16x16x32_bf16 v[48:51], v[156:159], v[164:167], v[48:51]
	v_mfma_f32_16x16x32_bf16 v[36:39], v[148:151], v[172:175], v[36:39]
	v_mfma_f32_16x16x32_bf16 v[32:35], v[156:159], v[172:175], v[32:35]
	v_mfma_f32_16x16x32_bf16 v[20:23], v[148:151], v[180:183], v[20:23]
	v_mfma_f32_16x16x32_bf16 v[16:19], v[156:159], v[180:183], v[16:19]
	v_mfma_f32_16x16x32_bf16 v[4:7], v[148:151], v[198:201], v[4:7]
	v_mfma_f32_16x16x32_bf16 v[0:3], v[156:159], v[198:201], v[0:3]
	v_mfma_f32_16x16x32_bf16 v[52:55], v[152:155], v[168:171], v[52:55]
	v_mfma_f32_16x16x32_bf16 v[48:51], v[160:163], v[168:171], v[48:51]
	v_mfma_f32_16x16x32_bf16 v[36:39], v[152:155], v[176:179], v[36:39]
	v_mfma_f32_16x16x32_bf16 v[32:35], v[160:163], v[176:179], v[32:35]
	v_mfma_f32_16x16x32_bf16 v[20:23], v[152:155], v[184:187], v[20:23]
	v_mfma_f32_16x16x32_bf16 v[16:19], v[160:163], v[184:187], v[16:19]
	v_mfma_f32_16x16x32_bf16 v[4:7], v[152:155], v[214:217], v[4:7]
	v_mfma_f32_16x16x32_bf16 v[0:3], v[160:163], v[214:217], v[0:3]
	s_setprio 0
	s_barrier
	s_add_i32 s85, 0, 0x18000
	v_add_u32_e32 v64, s85, v196
	s_add_i32 s87, 0, 0x1c000
	ds_read_b128 v[132:135], v64
	ds_read_b128 v[136:139], v64 offset:1024
	ds_read_b128 v[140:143], v64 offset:2048
	ds_read_b128 v[144:147], v64 offset:3072
	v_add_u32_e32 v64, s87, v196
	ds_read_b128 v[148:151], v64
	ds_read_b128 v[152:155], v64 offset:1024
	ds_read_b128 v[156:159], v64 offset:2048
	ds_read_b128 v[160:163], v64 offset:3072
	s_add_u32 s60, s2, 0x40000
	v_mov_b32_e32 v64, v192
	s_mov_b32 m0, s52
	ds_read_b128 v[164:167], v197 offset:32768
	ds_read_b128 v[168:171], v197 offset:33792
	ds_read_b128 v[172:175], v197 offset:34816
	ds_read_b128 v[176:179], v197 offset:35840
	ds_read_b128 v[180:183], v197 offset:36864
	ds_read_b128 v[184:187], v197 offset:37888
	ds_read_b128 v[198:201], v197 offset:38912
	ds_read_b128 v[214:217], v197 offset:39936
	s_addc_u32 s61, s3, 0
	s_nop 0
	global_load_lds_dwordx4 v64, s[60:61]
	v_mov_b32_e32 v64, v194
	s_mov_b32 m0, s53
	s_nop 0
	global_load_lds_dwordx4 v64, s[60:61]
	s_waitcnt vmcnt(8)
	s_waitcnt lgkmcnt(0)
	s_barrier
	s_setprio 1
	s_waitcnt lgkmcnt(0)
	v_mfma_f32_16x16x32_bf16 v[128:131], v[132:135], v[164:167], v[128:131]
	v_mfma_f32_16x16x32_bf16 v[124:127], v[140:143], v[164:167], v[124:127]
	v_mfma_f32_16x16x32_bf16 v[112:115], v[132:135], v[172:175], v[112:115]
	v_mfma_f32_16x16x32_bf16 v[108:111], v[140:143], v[172:175], v[108:111]
	v_mfma_f32_16x16x32_bf16 v[96:99], v[132:135], v[180:183], v[96:99]
	v_mfma_f32_16x16x32_bf16 v[92:95], v[140:143], v[180:183], v[92:95]
	v_mfma_f32_16x16x32_bf16 v[80:83], v[132:135], v[198:201], v[80:83]
	v_mfma_f32_16x16x32_bf16 v[76:79], v[140:143], v[198:201], v[76:79]
	v_mfma_f32_16x16x32_bf16 v[128:131], v[136:139], v[168:171], v[128:131]
	v_mfma_f32_16x16x32_bf16 v[124:127], v[144:147], v[168:171], v[124:127]
	v_mfma_f32_16x16x32_bf16 v[112:115], v[136:139], v[176:179], v[112:115]
	v_mfma_f32_16x16x32_bf16 v[108:111], v[144:147], v[176:179], v[108:111]
	v_mfma_f32_16x16x32_bf16 v[96:99], v[136:139], v[184:187], v[96:99]
	v_mfma_f32_16x16x32_bf16 v[92:95], v[144:147], v[184:187], v[92:95]
	v_mfma_f32_16x16x32_bf16 v[80:83], v[136:139], v[214:217], v[80:83]
	v_mfma_f32_16x16x32_bf16 v[76:79], v[144:147], v[214:217], v[76:79]
	v_mfma_f32_16x16x32_bf16 v[120:123], v[148:151], v[164:167], v[120:123]
	v_mfma_f32_16x16x32_bf16 v[116:119], v[156:159], v[164:167], v[116:119]
	v_mfma_f32_16x16x32_bf16 v[104:107], v[148:151], v[172:175], v[104:107]
	v_mfma_f32_16x16x32_bf16 v[100:103], v[156:159], v[172:175], v[100:103]
	v_mfma_f32_16x16x32_bf16 v[88:91], v[148:151], v[180:183], v[88:91]
	v_mfma_f32_16x16x32_bf16 v[84:87], v[156:159], v[180:183], v[84:87]
	v_mfma_f32_16x16x32_bf16 v[70:73], v[148:151], v[198:201], v[72:75]
	v_mfma_f32_16x16x32_bf16 v[66:69], v[156:159], v[198:201], v[66:69]
	v_mfma_f32_16x16x32_bf16 v[120:123], v[152:155], v[168:171], v[120:123]
	v_mfma_f32_16x16x32_bf16 v[116:119], v[160:163], v[168:171], v[116:119]
	v_mfma_f32_16x16x32_bf16 v[104:107], v[152:155], v[176:179], v[104:107]
	v_mfma_f32_16x16x32_bf16 v[100:103], v[160:163], v[176:179], v[100:103]
	v_mfma_f32_16x16x32_bf16 v[88:91], v[152:155], v[184:187], v[88:91]
	v_mfma_f32_16x16x32_bf16 v[84:87], v[160:163], v[184:187], v[84:87]
	v_mfma_f32_16x16x32_bf16 v[72:75], v[152:155], v[214:217], v[70:73]
	v_mfma_f32_16x16x32_bf16 v[68:71], v[160:163], v[214:217], v[66:69]
	s_setprio 0
	s_barrier
	v_mov_b32_e32 v64, v193
	ds_read_b128 v[164:167], v197 offset:49152
	ds_read_b128 v[168:171], v197 offset:50176
	ds_read_b128 v[172:175], v197 offset:51200
	ds_read_b128 v[176:179], v197 offset:52224
	ds_read_b128 v[180:183], v197 offset:53248
	ds_read_b128 v[184:187], v197 offset:54272
	ds_read_b128 v[198:201], v197 offset:55296
	ds_read_b128 v[214:217], v197 offset:56320
	s_add_i32 s60, s85, s49
	v_lshl_add_u64 v[66:67], s[54:55], 0, v[64:65]
	v_lshl_add_u64 v[66:67], v[66:67], 0, s[24:25]
	s_mov_b32 m0, s60
	v_mov_b32_e32 v64, v195
	global_load_lds_dwordx4 v[66:67], off
	s_add_i32 m0, s60, 0x2000
	s_nop 0
	v_lshl_add_u64 v[66:67], s[54:55], 0, v[64:65]
	s_add_u32 s54, s54, 0x20080
	v_lshl_add_u64 v[66:67], v[66:67], 0, s[24:25]
	s_addc_u32 s55, s55, 0
	v_mov_b32_e32 v64, v193
	s_add_i32 s60, s87, s49
	global_load_lds_dwordx4 v[66:67], off
	s_mov_b32 m0, s60
	s_nop 0
	global_load_lds_dwordx4 v64, s[54:55]
	v_mov_b32_e32 v64, v195
	s_add_i32 m0, s60, 0x2000
	s_nop 0
	global_load_lds_dwordx4 v64, s[54:55]
	v_mov_b32_e32 v64, v192
	s_mov_b32 m0, s22
	v_lshl_add_u64 v[66:67], s[2:3], 0, v[64:65]
	v_lshl_add_u64 v[66:67], v[66:67], 0, s[24:25]
	v_mov_b32_e32 v64, v194
	global_load_lds_dwordx4 v[66:67], off
	s_mov_b32 m0, s58
	v_lshl_add_u64 v[66:67], s[2:3], 0, v[64:65]
	v_lshl_add_u64 v[66:67], v[66:67], 0, s[24:25]
	global_load_lds_dwordx4 v[66:67], off
	s_waitcnt vmcnt(8)
	s_waitcnt lgkmcnt(0)
	s_barrier
	s_setprio 1
	s_waitcnt lgkmcnt(0)
	v_mfma_f32_16x16x32_bf16 v[60:63], v[132:135], v[164:167], v[60:63]
	v_mfma_f32_16x16x32_bf16 v[56:59], v[140:143], v[164:167], v[56:59]
	v_mfma_f32_16x16x32_bf16 v[44:47], v[132:135], v[172:175], v[44:47]
	v_mfma_f32_16x16x32_bf16 v[40:43], v[140:143], v[172:175], v[40:43]
	v_mfma_f32_16x16x32_bf16 v[28:31], v[132:135], v[180:183], v[28:31]
	v_mfma_f32_16x16x32_bf16 v[24:27], v[140:143], v[180:183], v[24:27]
	v_mfma_f32_16x16x32_bf16 v[12:15], v[132:135], v[198:201], v[12:15]
	v_mfma_f32_16x16x32_bf16 v[8:11], v[140:143], v[198:201], v[8:11]
	v_mfma_f32_16x16x32_bf16 v[60:63], v[136:139], v[168:171], v[60:63]
	v_mfma_f32_16x16x32_bf16 v[56:59], v[144:147], v[168:171], v[56:59]
	v_mfma_f32_16x16x32_bf16 v[44:47], v[136:139], v[176:179], v[44:47]
	v_mfma_f32_16x16x32_bf16 v[40:43], v[144:147], v[176:179], v[40:43]
	v_mfma_f32_16x16x32_bf16 v[28:31], v[136:139], v[184:187], v[28:31]
	v_mfma_f32_16x16x32_bf16 v[24:27], v[144:147], v[184:187], v[24:27]
	v_mfma_f32_16x16x32_bf16 v[12:15], v[136:139], v[214:217], v[12:15]
	v_mfma_f32_16x16x32_bf16 v[8:11], v[144:147], v[214:217], v[8:11]
	v_mfma_f32_16x16x32_bf16 v[52:55], v[148:151], v[164:167], v[52:55]
	v_mfma_f32_16x16x32_bf16 v[48:51], v[156:159], v[164:167], v[48:51]
	v_mfma_f32_16x16x32_bf16 v[36:39], v[148:151], v[172:175], v[36:39]
	v_mfma_f32_16x16x32_bf16 v[32:35], v[156:159], v[172:175], v[32:35]
	v_mfma_f32_16x16x32_bf16 v[20:23], v[148:151], v[180:183], v[20:23]
	v_mfma_f32_16x16x32_bf16 v[16:19], v[156:159], v[180:183], v[16:19]
	v_mfma_f32_16x16x32_bf16 v[4:7], v[148:151], v[198:201], v[4:7]
	v_mfma_f32_16x16x32_bf16 v[0:3], v[156:159], v[198:201], v[0:3]
	v_mfma_f32_16x16x32_bf16 v[52:55], v[152:155], v[168:171], v[52:55]
	v_mfma_f32_16x16x32_bf16 v[48:51], v[160:163], v[168:171], v[48:51]
	v_mfma_f32_16x16x32_bf16 v[36:39], v[152:155], v[176:179], v[36:39]
	v_mfma_f32_16x16x32_bf16 v[32:35], v[160:163], v[176:179], v[32:35]
	v_mfma_f32_16x16x32_bf16 v[20:23], v[152:155], v[184:187], v[20:23]
	v_mfma_f32_16x16x32_bf16 v[16:19], v[160:163], v[184:187], v[16:19]
	v_mfma_f32_16x16x32_bf16 v[4:7], v[152:155], v[214:217], v[4:7]
	v_mfma_f32_16x16x32_bf16 v[0:3], v[160:163], v[214:217], v[0:3]
	s_setprio 0
	s_barrier
	s_add_u32 s94, s94, 0x100
	s_addc_u32 s95, 0, s95
	s_cmp_gt_u32 s77, 13
	s_cbranch_scc1 .LBB0_148

.LBB0_324:
	s_add_i32 s60, 0, 0x10000
	s_add_i32 s67, 0, 0x14000
	v_add_u32_e32 v64, s60, v140
	ds_read_b128 v[130:133], v64
	ds_read_b128 v[142:145], v64 offset:1024
	ds_read_b128 v[146:149], v64 offset:2048
	ds_read_b128 v[150:153], v64 offset:3072
	v_add_u32_e32 v64, s67, v140
	ds_read_b128 v[154:157], v64
	ds_read_b128 v[158:161], v64 offset:1024
	ds_read_b128 v[162:165], v64 offset:2048
	ds_read_b128 v[166:169], v64 offset:3072
	s_add_u32 s2, s94, 0xfffc0080
	s_addc_u32 s3, s95, -1
	s_cmp_eq_u32 s66, 12
	s_cselect_b32 s3, s41, s3
	s_cselect_b32 s2, s43, s2
	s_cselect_b32 s55, s62, s65
	s_cselect_b32 s54, s63, s64
	v_mov_b32_e32 v64, v136
	ds_read_b128 v[170:173], v141
	ds_read_b128 v[174:177], v141 offset:1024
	ds_read_b128 v[178:181], v141 offset:2048
	ds_read_b128 v[182:185], v141 offset:3072
	ds_read_b128 v[190:193], v141 offset:4096
	ds_read_b128 v[194:197], v141 offset:5120
	ds_read_b128 v[214:217], v141 offset:6144
	ds_read_b128 v[218:221], v141 offset:7168
	s_add_i32 m0, s17, 0xc000
	s_nop 0
	global_load_lds_dwordx4 v64, s[94:95]
	v_mov_b32_e32 v64, v138
	s_add_i32 m0, s17, 0xe000
	s_nop 0
	global_load_lds_dwordx4 v64, s[94:95]
	s_waitcnt vmcnt(8)
	s_waitcnt lgkmcnt(0)
	s_barrier
	s_setprio 1
	s_waitcnt lgkmcnt(0)
	v_mfma_f32_16x16x32_bf16 v[126:129], v[130:133], v[170:173], v[126:129]
	v_mfma_f32_16x16x32_bf16 v[122:125], v[146:149], v[170:173], v[122:125]
	v_mfma_f32_16x16x32_bf16 v[110:113], v[130:133], v[178:181], v[110:113]
	v_mfma_f32_16x16x32_bf16 v[106:109], v[146:149], v[178:181], v[106:109]
	v_mfma_f32_16x16x32_bf16 v[94:97], v[130:133], v[190:193], v[94:97]
	v_mfma_f32_16x16x32_bf16 v[90:93], v[146:149], v[190:193], v[90:93]
	v_mfma_f32_16x16x32_bf16 v[78:81], v[130:133], v[214:217], v[78:81]
	v_mfma_f32_16x16x32_bf16 v[74:77], v[146:149], v[214:217], v[74:77]
	v_mfma_f32_16x16x32_bf16 v[126:129], v[142:145], v[174:177], v[126:129]
	v_mfma_f32_16x16x32_bf16 v[122:125], v[150:153], v[174:177], v[122:125]
	v_mfma_f32_16x16x32_bf16 v[110:113], v[142:145], v[182:185], v[110:113]
	v_mfma_f32_16x16x32_bf16 v[106:109], v[150:153], v[182:185], v[106:109]
	v_mfma_f32_16x16x32_bf16 v[94:97], v[142:145], v[194:197], v[94:97]
	v_mfma_f32_16x16x32_bf16 v[90:93], v[150:153], v[194:197], v[90:93]
	v_mfma_f32_16x16x32_bf16 v[78:81], v[142:145], v[218:221], v[78:81]
	v_mfma_f32_16x16x32_bf16 v[74:77], v[150:153], v[218:221], v[74:77]
	v_mfma_f32_16x16x32_bf16 v[118:121], v[154:157], v[170:173], v[118:121]
	v_mfma_f32_16x16x32_bf16 v[114:117], v[162:165], v[170:173], v[114:117]
	v_mfma_f32_16x16x32_bf16 v[102:105], v[154:157], v[178:181], v[102:105]
	v_mfma_f32_16x16x32_bf16 v[98:101], v[162:165], v[178:181], v[98:101]
	v_mfma_f32_16x16x32_bf16 v[86:89], v[154:157], v[190:193], v[86:89]
	v_mfma_f32_16x16x32_bf16 v[82:85], v[162:165], v[190:193], v[82:85]
	v_mfma_f32_16x16x32_bf16 v[70:73], v[154:157], v[214:217], v[70:73]
	v_mfma_f32_16x16x32_bf16 v[66:69], v[162:165], v[214:217], v[66:69]
	v_mfma_f32_16x16x32_bf16 v[118:121], v[158:161], v[174:177], v[118:121]
	v_mfma_f32_16x16x32_bf16 v[114:117], v[166:169], v[174:177], v[114:117]
	v_mfma_f32_16x16x32_bf16 v[102:105], v[158:161], v[182:185], v[102:105]
	v_mfma_f32_16x16x32_bf16 v[98:101], v[166:169], v[182:185], v[98:101]
	v_mfma_f32_16x16x32_bf16 v[86:89], v[158:161], v[194:197], v[86:89]
	v_mfma_f32_16x16x32_bf16 v[82:85], v[166:169], v[194:197], v[82:85]
	v_mfma_f32_16x16x32_bf16 v[70:73], v[158:161], v[218:221], v[70:73]
	v_mfma_f32_16x16x32_bf16 v[66:69], v[166:169], v[218:221], v[66:69]
	s_setprio 0
	s_barrier
	v_mov_b32_e32 v64, v137
	s_add_i32 s60, s60, s11
	ds_read_b128 v[170:173], v141 offset:16384
	ds_read_b128 v[174:177], v141 offset:17408
	ds_read_b128 v[178:181], v141 offset:18432
	ds_read_b128 v[182:185], v141 offset:19456
	ds_read_b128 v[190:193], v141 offset:20480
	ds_read_b128 v[194:197], v141 offset:21504
	ds_read_b128 v[214:217], v141 offset:22528
	ds_read_b128 v[218:221], v141 offset:23552
	s_mov_b32 m0, s60
	s_nop 0
	global_load_lds_dwordx4 v64, s[54:55]
	v_mov_b32_e32 v64, v139
	s_add_i32 m0, s60, 0x2000
	s_add_u32 s60, s54, 0x40000
	global_load_lds_dwordx4 v64, s[54:55]
	s_addc_u32 s61, s55, 0
	v_mov_b32_e32 v64, v137
	s_add_i32 s67, s67, s11
	s_mov_b32 m0, s67
	s_nop 0
	global_load_lds_dwordx4 v64, s[60:61]
	v_mov_b32_e32 v64, v139
	s_add_i32 m0, s67, 0x2000
	s_nop 0
	global_load_lds_dwordx4 v64, s[60:61]
	v_mov_b32_e32 v64, v136
	s_mov_b32 m0, s17
	s_nop 0
	global_load_lds_dwordx4 v64, s[2:3]
	v_mov_b32_e32 v64, v138
	s_mov_b32 m0, s22
	s_nop 0
	global_load_lds_dwordx4 v64, s[2:3]
	s_waitcnt vmcnt(8)
	s_waitcnt lgkmcnt(0)
	s_barrier
	s_setprio 1
	s_waitcnt lgkmcnt(0)
	v_mfma_f32_16x16x32_bf16 v[60:63], v[130:133], v[170:173], v[60:63]
	v_mfma_f32_16x16x32_bf16 v[56:59], v[146:149], v[170:173], v[56:59]
	v_mfma_f32_16x16x32_bf16 v[44:47], v[130:133], v[178:181], v[44:47]
	v_mfma_f32_16x16x32_bf16 v[40:43], v[146:149], v[178:181], v[40:43]
	v_mfma_f32_16x16x32_bf16 v[28:31], v[130:133], v[190:193], v[28:31]
	v_mfma_f32_16x16x32_bf16 v[24:27], v[146:149], v[190:193], v[24:27]
	v_mfma_f32_16x16x32_bf16 v[12:15], v[130:133], v[214:217], v[12:15]
	v_mfma_f32_16x16x32_bf16 v[8:11], v[146:149], v[214:217], v[8:11]
	v_mfma_f32_16x16x32_bf16 v[60:63], v[142:145], v[174:177], v[60:63]
	v_mfma_f32_16x16x32_bf16 v[56:59], v[150:153], v[174:177], v[56:59]
	v_mfma_f32_16x16x32_bf16 v[44:47], v[142:145], v[182:185], v[44:47]
	v_mfma_f32_16x16x32_bf16 v[40:43], v[150:153], v[182:185], v[40:43]
	v_mfma_f32_16x16x32_bf16 v[28:31], v[142:145], v[194:197], v[28:31]
	v_mfma_f32_16x16x32_bf16 v[24:27], v[150:153], v[194:197], v[24:27]
	v_mfma_f32_16x16x32_bf16 v[12:15], v[142:145], v[218:221], v[12:15]
	v_mfma_f32_16x16x32_bf16 v[8:11], v[150:153], v[218:221], v[8:11]
	v_mfma_f32_16x16x32_bf16 v[52:55], v[154:157], v[170:173], v[52:55]
	v_mfma_f32_16x16x32_bf16 v[48:51], v[162:165], v[170:173], v[48:51]
	v_mfma_f32_16x16x32_bf16 v[36:39], v[154:157], v[178:181], v[36:39]
	v_mfma_f32_16x16x32_bf16 v[32:35], v[162:165], v[178:181], v[32:35]
	v_mfma_f32_16x16x32_bf16 v[20:23], v[154:157], v[190:193], v[20:23]
	v_mfma_f32_16x16x32_bf16 v[16:19], v[162:165], v[190:193], v[16:19]
	v_mfma_f32_16x16x32_bf16 v[4:7], v[154:157], v[214:217], v[4:7]
	v_mfma_f32_16x16x32_bf16 v[0:3], v[162:165], v[214:217], v[0:3]
	v_mfma_f32_16x16x32_bf16 v[52:55], v[158:161], v[174:177], v[52:55]
	v_mfma_f32_16x16x32_bf16 v[48:51], v[166:169], v[174:177], v[48:51]
	v_mfma_f32_16x16x32_bf16 v[36:39], v[158:161], v[182:185], v[36:39]
	v_mfma_f32_16x16x32_bf16 v[32:35], v[166:169], v[182:185], v[32:35]
	v_mfma_f32_16x16x32_bf16 v[20:23], v[158:161], v[194:197], v[20:23]
	v_mfma_f32_16x16x32_bf16 v[16:19], v[166:169], v[194:197], v[16:19]
	v_mfma_f32_16x16x32_bf16 v[4:7], v[158:161], v[218:221], v[4:7]
	v_mfma_f32_16x16x32_bf16 v[0:3], v[166:169], v[218:221], v[0:3]
	s_setprio 0
	s_barrier
	s_add_i32 s67, 0, 0x18000
	v_add_u32_e32 v64, s67, v140
	s_add_i32 s68, 0, 0x1c000
	ds_read_b128 v[130:133], v64
	ds_read_b128 v[142:145], v64 offset:1024
	ds_read_b128 v[146:149], v64 offset:2048
	ds_read_b128 v[150:153], v64 offset:3072
	v_add_u32_e32 v64, s68, v140
	ds_read_b128 v[154:157], v64
	ds_read_b128 v[158:161], v64 offset:1024
	ds_read_b128 v[162:165], v64 offset:2048
	ds_read_b128 v[166:169], v64 offset:3072
	s_add_u32 s60, s2, 0x40000
	v_mov_b32_e32 v64, v136
	s_mov_b32 m0, s49
	ds_read_b128 v[170:173], v141 offset:32768
	ds_read_b128 v[174:177], v141 offset:33792
	ds_read_b128 v[178:181], v141 offset:34816
	ds_read_b128 v[182:185], v141 offset:35840
	ds_read_b128 v[190:193], v141 offset:36864
	ds_read_b128 v[194:197], v141 offset:37888
	ds_read_b128 v[214:217], v141 offset:38912
	ds_read_b128 v[218:221], v141 offset:39936
	s_addc_u32 s61, s3, 0
	s_nop 0
	global_load_lds_dwordx4 v64, s[60:61]
	v_mov_b32_e32 v64, v138
	s_mov_b32 m0, s50
	s_nop 0
	global_load_lds_dwordx4 v64, s[60:61]
	s_waitcnt vmcnt(8)
	s_waitcnt lgkmcnt(0)
	s_barrier
	s_setprio 1
	s_waitcnt lgkmcnt(0)
	v_mfma_f32_16x16x32_bf16 v[126:129], v[130:133], v[170:173], v[126:129]
	v_mfma_f32_16x16x32_bf16 v[122:125], v[146:149], v[170:173], v[122:125]
	v_mfma_f32_16x16x32_bf16 v[110:113], v[130:133], v[178:181], v[110:113]
	v_mfma_f32_16x16x32_bf16 v[106:109], v[146:149], v[178:181], v[106:109]
	v_mfma_f32_16x16x32_bf16 v[94:97], v[130:133], v[190:193], v[94:97]
	v_mfma_f32_16x16x32_bf16 v[90:93], v[146:149], v[190:193], v[90:93]
	v_mfma_f32_16x16x32_bf16 v[78:81], v[130:133], v[214:217], v[78:81]
	v_mfma_f32_16x16x32_bf16 v[74:77], v[146:149], v[214:217], v[74:77]
	v_mfma_f32_16x16x32_bf16 v[126:129], v[142:145], v[174:177], v[126:129]
	v_mfma_f32_16x16x32_bf16 v[122:125], v[150:153], v[174:177], v[122:125]
	v_mfma_f32_16x16x32_bf16 v[110:113], v[142:145], v[182:185], v[110:113]
	v_mfma_f32_16x16x32_bf16 v[106:109], v[150:153], v[182:185], v[106:109]
	v_mfma_f32_16x16x32_bf16 v[94:97], v[142:145], v[194:197], v[94:97]
	v_mfma_f32_16x16x32_bf16 v[90:93], v[150:153], v[194:197], v[90:93]
	v_mfma_f32_16x16x32_bf16 v[78:81], v[142:145], v[218:221], v[78:81]
	v_mfma_f32_16x16x32_bf16 v[74:77], v[150:153], v[218:221], v[74:77]
	v_mfma_f32_16x16x32_bf16 v[118:121], v[154:157], v[170:173], v[118:121]
	v_mfma_f32_16x16x32_bf16 v[114:117], v[162:165], v[170:173], v[114:117]
	v_mfma_f32_16x16x32_bf16 v[102:105], v[154:157], v[178:181], v[102:105]
	v_mfma_f32_16x16x32_bf16 v[98:101], v[162:165], v[178:181], v[98:101]
	v_mfma_f32_16x16x32_bf16 v[86:89], v[154:157], v[190:193], v[86:89]
	v_mfma_f32_16x16x32_bf16 v[82:85], v[162:165], v[190:193], v[82:85]
	v_mfma_f32_16x16x32_bf16 v[70:73], v[154:157], v[214:217], v[70:73]
	v_mfma_f32_16x16x32_bf16 v[66:69], v[162:165], v[214:217], v[66:69]
	v_mfma_f32_16x16x32_bf16 v[118:121], v[158:161], v[174:177], v[118:121]
	v_mfma_f32_16x16x32_bf16 v[114:117], v[166:169], v[174:177], v[114:117]
	v_mfma_f32_16x16x32_bf16 v[102:105], v[158:161], v[182:185], v[102:105]
	v_mfma_f32_16x16x32_bf16 v[98:101], v[166:169], v[182:185], v[98:101]
	v_mfma_f32_16x16x32_bf16 v[86:89], v[158:161], v[194:197], v[86:89]
	v_mfma_f32_16x16x32_bf16 v[82:85], v[166:169], v[194:197], v[82:85]
	v_mfma_f32_16x16x32_bf16 v[70:73], v[158:161], v[218:221], v[70:73]
	v_mfma_f32_16x16x32_bf16 v[66:69], v[166:169], v[218:221], v[66:69]
	s_setprio 0
	s_barrier
	v_mov_b32_e32 v64, v137
	ds_read_b128 v[170:173], v141 offset:49152
	ds_read_b128 v[174:177], v141 offset:50176
	ds_read_b128 v[178:181], v141 offset:51200
	ds_read_b128 v[182:185], v141 offset:52224
	ds_read_b128 v[190:193], v141 offset:53248
	ds_read_b128 v[194:197], v141 offset:54272
	ds_read_b128 v[214:217], v141 offset:55296
	ds_read_b128 v[218:221], v141 offset:56320
	s_add_i32 s60, s67, s11
	v_lshl_add_u64 v[134:135], s[54:55], 0, v[64:65]
	v_lshl_add_u64 v[134:135], v[134:135], 0, s[24:25]
	s_mov_b32 m0, s60
	v_mov_b32_e32 v64, v139
	global_load_lds_dwordx4 v[134:135], off
	s_add_i32 m0, s60, 0x2000
	s_nop 0
	v_lshl_add_u64 v[134:135], s[54:55], 0, v[64:65]
	s_add_u32 s54, s54, 0x40080
	v_lshl_add_u64 v[134:135], v[134:135], 0, s[24:25]
	s_addc_u32 s55, s55, 0
	v_mov_b32_e32 v64, v137
	s_add_i32 s60, s68, s11
	global_load_lds_dwordx4 v[134:135], off
	s_mov_b32 m0, s60
	s_nop 0
	global_load_lds_dwordx4 v64, s[54:55]
	v_mov_b32_e32 v64, v139
	s_add_i32 m0, s60, 0x2000
	s_nop 0
	global_load_lds_dwordx4 v64, s[54:55]
	v_mov_b32_e32 v64, v136
	s_mov_b32 m0, s51
	v_lshl_add_u64 v[134:135], s[2:3], 0, v[64:65]
	v_lshl_add_u64 v[134:135], v[134:135], 0, s[24:25]
	v_mov_b32_e32 v64, v138
	global_load_lds_dwordx4 v[134:135], off
	s_mov_b32 m0, s52
	v_lshl_add_u64 v[134:135], s[2:3], 0, v[64:65]
	v_lshl_add_u64 v[134:135], v[134:135], 0, s[24:25]
	global_load_lds_dwordx4 v[134:135], off
	s_waitcnt vmcnt(8)
	s_waitcnt lgkmcnt(0)
	s_barrier
	s_setprio 1
	s_waitcnt lgkmcnt(0)
	v_mfma_f32_16x16x32_bf16 v[60:63], v[130:133], v[170:173], v[60:63]
	v_mfma_f32_16x16x32_bf16 v[56:59], v[146:149], v[170:173], v[56:59]
	v_mfma_f32_16x16x32_bf16 v[44:47], v[130:133], v[178:181], v[44:47]
	v_mfma_f32_16x16x32_bf16 v[40:43], v[146:149], v[178:181], v[40:43]
	v_mfma_f32_16x16x32_bf16 v[28:31], v[130:133], v[190:193], v[28:31]
	v_mfma_f32_16x16x32_bf16 v[24:27], v[146:149], v[190:193], v[24:27]
	v_mfma_f32_16x16x32_bf16 v[12:15], v[130:133], v[214:217], v[12:15]
	v_mfma_f32_16x16x32_bf16 v[8:11], v[146:149], v[214:217], v[8:11]
	v_mfma_f32_16x16x32_bf16 v[60:63], v[142:145], v[174:177], v[60:63]
	v_mfma_f32_16x16x32_bf16 v[56:59], v[150:153], v[174:177], v[56:59]
	v_mfma_f32_16x16x32_bf16 v[44:47], v[142:145], v[182:185], v[44:47]
	v_mfma_f32_16x16x32_bf16 v[40:43], v[150:153], v[182:185], v[40:43]
	v_mfma_f32_16x16x32_bf16 v[28:31], v[142:145], v[194:197], v[28:31]
	v_mfma_f32_16x16x32_bf16 v[24:27], v[150:153], v[194:197], v[24:27]
	v_mfma_f32_16x16x32_bf16 v[12:15], v[142:145], v[218:221], v[12:15]
	v_mfma_f32_16x16x32_bf16 v[8:11], v[150:153], v[218:221], v[8:11]
	v_mfma_f32_16x16x32_bf16 v[52:55], v[154:157], v[170:173], v[52:55]
	v_mfma_f32_16x16x32_bf16 v[48:51], v[162:165], v[170:173], v[48:51]
	v_mfma_f32_16x16x32_bf16 v[36:39], v[154:157], v[178:181], v[36:39]
	v_mfma_f32_16x16x32_bf16 v[32:35], v[162:165], v[178:181], v[32:35]
	v_mfma_f32_16x16x32_bf16 v[20:23], v[154:157], v[190:193], v[20:23]
	v_mfma_f32_16x16x32_bf16 v[16:19], v[162:165], v[190:193], v[16:19]
	v_mfma_f32_16x16x32_bf16 v[4:7], v[154:157], v[214:217], v[4:7]
	v_mfma_f32_16x16x32_bf16 v[0:3], v[162:165], v[214:217], v[0:3]
	v_mfma_f32_16x16x32_bf16 v[52:55], v[158:161], v[174:177], v[52:55]
	v_mfma_f32_16x16x32_bf16 v[48:51], v[166:169], v[174:177], v[48:51]
	v_mfma_f32_16x16x32_bf16 v[36:39], v[158:161], v[182:185], v[36:39]
	v_mfma_f32_16x16x32_bf16 v[32:35], v[166:169], v[182:185], v[32:35]
	v_mfma_f32_16x16x32_bf16 v[20:23], v[158:161], v[194:197], v[20:23]
	v_mfma_f32_16x16x32_bf16 v[16:19], v[166:169], v[194:197], v[16:19]
	v_mfma_f32_16x16x32_bf16 v[4:7], v[158:161], v[218:221], v[4:7]
	v_mfma_f32_16x16x32_bf16 v[0:3], v[166:169], v[218:221], v[0:3]
	s_setprio 0
	s_barrier
	s_add_i32 s66, s66, 2
	s_add_u32 s94, s94, 0x100
	s_addc_u32 s95, s95, 0
	s_add_u32 s64, s64, 0x100
	s_addc_u32 s65, s65, 0
	s_cmp_gt_u32 s66, 13
	s_cbranch_scc0 .LBB0_324
	s_and_b64 vcc, exec, s[82:83]
	s_movk_i32 s62, 0x89f
	s_movk_i32 s63, 0xca0
	s_cbranch_vccz .LBB0_327
	s_barrier

.LBB0_695:
	s_add_i32 s60, 0, 0x10000
	s_add_i32 s61, 0, 0x14000
	v_add_u32_e32 v64, s60, v134
	ds_read_b128 v[136:139], v64
	ds_read_b128 v[140:143], v64 offset:1024
	ds_read_b128 v[144:147], v64 offset:2048
	ds_read_b128 v[148:151], v64 offset:3072
	v_add_u32_e32 v64, s61, v134
	ds_read_b128 v[152:155], v64
	ds_read_b128 v[156:159], v64 offset:1024
	ds_read_b128 v[160:163], v64 offset:2048
	ds_read_b128 v[164:167], v64 offset:3072
	s_add_u32 s2, s88, 0xfda00080
	s_addc_u32 s3, s89, -1
	s_cmp_lg_u32 s57, 60
	s_cselect_b32 s54, s2, 0
	s_cselect_b32 s55, s3, 0
	s_add_u32 s2, s86, s54
	s_addc_u32 s3, s87, s55
	s_add_u32 s54, s46, s54
	s_addc_u32 s55, s47, s55
	s_add_i32 m0, s17, 0xc000
	v_mov_b32_e32 v64, v130
	s_add_u32 s58, s53, s88
	ds_read_b128 v[168:171], v135
	ds_read_b128 v[172:175], v135 offset:1024
	ds_read_b128 v[176:179], v135 offset:2048
	ds_read_b128 v[180:183], v135 offset:3072
	ds_read_b128 v[184:187], v135 offset:4096
	ds_read_b128 v[190:193], v135 offset:5120
	ds_read_b128 v[194:197], v135 offset:6144
	ds_read_b128 v[198:201], v135 offset:7168
	s_addc_u32 s59, s56, s89
	global_load_lds_dwordx4 v64, s[58:59]
	v_mov_b32_e32 v64, v132
	s_add_i32 m0, s17, 0xe000
	s_nop 0
	global_load_lds_dwordx4 v64, s[58:59]
	s_waitcnt vmcnt(8)
	s_waitcnt lgkmcnt(0)
	s_barrier
	s_setprio 1
	s_waitcnt lgkmcnt(0)
	v_mfma_f32_16x16x32_bf16 v[48:51], v[136:139], v[168:171], v[48:51]
	v_mfma_f32_16x16x32_bf16 v[44:47], v[144:147], v[168:171], v[44:47]
	v_mfma_f32_16x16x32_bf16 v[4:7], v[136:139], v[176:179], v[4:7]
	v_mfma_f32_16x16x32_bf16 v[0:3], v[144:147], v[176:179], v[0:3]
	v_mfma_f32_16x16x32_bf16 v[36:39], v[136:139], v[184:187], v[36:39]
	v_mfma_f32_16x16x32_bf16 v[32:35], v[144:147], v[184:187], v[32:35]
	v_mfma_f32_16x16x32_bf16 v[78:81], v[136:139], v[194:197], v[78:81]
	v_mfma_f32_16x16x32_bf16 v[74:77], v[144:147], v[194:197], v[74:77]
	v_mfma_f32_16x16x32_bf16 v[48:51], v[140:143], v[172:175], v[48:51]
	v_mfma_f32_16x16x32_bf16 v[44:47], v[148:151], v[172:175], v[44:47]
	v_mfma_f32_16x16x32_bf16 v[4:7], v[140:143], v[180:183], v[4:7]
	v_mfma_f32_16x16x32_bf16 v[0:3], v[148:151], v[180:183], v[0:3]
	v_mfma_f32_16x16x32_bf16 v[36:39], v[140:143], v[190:193], v[36:39]
	v_mfma_f32_16x16x32_bf16 v[32:35], v[148:151], v[190:193], v[32:35]
	v_mfma_f32_16x16x32_bf16 v[78:81], v[140:143], v[198:201], v[78:81]
	v_mfma_f32_16x16x32_bf16 v[74:77], v[148:151], v[198:201], v[74:77]
	v_mfma_f32_16x16x32_bf16 v[16:19], v[152:155], v[168:171], v[16:19]
	v_mfma_f32_16x16x32_bf16 v[8:11], v[160:163], v[168:171], v[8:11]
	v_mfma_f32_16x16x32_bf16 v[24:27], v[152:155], v[176:179], v[24:27]
	v_mfma_f32_16x16x32_bf16 v[28:31], v[160:163], v[176:179], v[28:31]
	v_mfma_f32_16x16x32_bf16 v[56:59], v[152:155], v[184:187], v[56:59]
	v_mfma_f32_16x16x32_bf16 v[66:69], v[160:163], v[184:187], v[66:69]
	v_mfma_f32_16x16x32_bf16 v[86:89], v[152:155], v[194:197], v[86:89]
	v_mfma_f32_16x16x32_bf16 v[94:97], v[160:163], v[194:197], v[94:97]
	v_mfma_f32_16x16x32_bf16 v[16:19], v[156:159], v[172:175], v[16:19]
	v_mfma_f32_16x16x32_bf16 v[8:11], v[164:167], v[172:175], v[8:11]
	v_mfma_f32_16x16x32_bf16 v[24:27], v[156:159], v[180:183], v[24:27]
	v_mfma_f32_16x16x32_bf16 v[28:31], v[164:167], v[180:183], v[28:31]
	v_mfma_f32_16x16x32_bf16 v[56:59], v[156:159], v[190:193], v[56:59]
	v_mfma_f32_16x16x32_bf16 v[66:69], v[164:167], v[190:193], v[66:69]
	v_mfma_f32_16x16x32_bf16 v[86:89], v[156:159], v[198:201], v[86:89]
	v_mfma_f32_16x16x32_bf16 v[94:97], v[164:167], v[198:201], v[94:97]
	s_setprio 0
	s_barrier
	v_mov_b32_e32 v64, v130
	s_mov_b32 m0, s17
	s_nop 0
	global_load_lds_dwordx4 v64, s[2:3]
	v_mov_b32_e32 v64, v132
	s_mov_b32 m0, s41
	s_nop 0
	global_load_lds_dwordx4 v64, s[2:3]
	v_mov_b32_e32 v64, v131
	s_add_i32 s58, s60, s11
	ds_read_b128 v[168:171], v135 offset:16384
	ds_read_b128 v[172:175], v135 offset:17408
	ds_read_b128 v[176:179], v135 offset:18432
	ds_read_b128 v[180:183], v135 offset:19456
	ds_read_b128 v[184:187], v135 offset:20480
	ds_read_b128 v[190:193], v135 offset:21504
	ds_read_b128 v[194:197], v135 offset:22528
	ds_read_b128 v[198:201], v135 offset:23552
	s_mov_b32 m0, s58
	s_nop 0
	global_load_lds_dwordx4 v64, s[54:55]
	v_mov_b32_e32 v64, v133
	s_add_i32 m0, s58, 0x2000
	s_add_u32 s58, s54, 0x100000
	global_load_lds_dwordx4 v64, s[54:55]
	s_addc_u32 s59, s55, 0
	v_mov_b32_e32 v64, v131
	s_add_i32 s60, s61, s11
	s_mov_b32 m0, s60
	s_nop 0
	global_load_lds_dwordx4 v64, s[58:59]
	v_mov_b32_e32 v64, v133
	s_add_i32 m0, s60, 0x2000
	s_nop 0
	global_load_lds_dwordx4 v64, s[58:59]
	s_waitcnt vmcnt(8)
	s_waitcnt lgkmcnt(0)
	s_barrier
	s_setprio 1
	s_waitcnt lgkmcnt(0)
	v_mfma_f32_16x16x32_bf16 v[106:109], v[136:139], v[168:171], v[106:109]
	v_mfma_f32_16x16x32_bf16 v[102:105], v[144:147], v[168:171], v[102:105]
	v_mfma_f32_16x16x32_bf16 v[126:129], v[136:139], v[176:179], v[126:129]
	v_mfma_f32_16x16x32_bf16 v[122:125], v[144:147], v[176:179], v[122:125]
	v_mfma_f32_16x16x32_bf16 v[90:93], v[136:139], v[184:187], v[90:93]
	v_mfma_f32_16x16x32_bf16 v[82:85], v[144:147], v[184:187], v[82:85]
	v_mfma_f32_16x16x32_bf16 v[52:55], v[136:139], v[194:197], v[52:55]
	v_mfma_f32_16x16x32_bf16 v[40:43], v[144:147], v[194:197], v[40:43]
	v_mfma_f32_16x16x32_bf16 v[106:109], v[140:143], v[172:175], v[106:109]
	v_mfma_f32_16x16x32_bf16 v[102:105], v[148:151], v[172:175], v[102:105]
	v_mfma_f32_16x16x32_bf16 v[126:129], v[140:143], v[180:183], v[126:129]
	v_mfma_f32_16x16x32_bf16 v[122:125], v[148:151], v[180:183], v[122:125]
	v_mfma_f32_16x16x32_bf16 v[90:93], v[140:143], v[190:193], v[90:93]
	v_mfma_f32_16x16x32_bf16 v[82:85], v[148:151], v[190:193], v[82:85]
	v_mfma_f32_16x16x32_bf16 v[52:55], v[140:143], v[198:201], v[52:55]
	v_mfma_f32_16x16x32_bf16 v[40:43], v[148:151], v[198:201], v[40:43]
	v_mfma_f32_16x16x32_bf16 v[114:117], v[152:155], v[168:171], v[114:117]
	v_mfma_f32_16x16x32_bf16 v[118:121], v[160:163], v[168:171], v[118:121]
	v_mfma_f32_16x16x32_bf16 v[110:113], v[152:155], v[176:179], v[110:113]
	v_mfma_f32_16x16x32_bf16 v[98:101], v[160:163], v[176:179], v[98:101]
	v_mfma_f32_16x16x32_bf16 v[70:73], v[152:155], v[184:187], v[70:73]
	v_mfma_f32_16x16x32_bf16 v[60:63], v[160:163], v[184:187], v[60:63]
	v_mfma_f32_16x16x32_bf16 v[20:23], v[152:155], v[194:197], v[20:23]
	v_mfma_f32_16x16x32_bf16 v[12:15], v[160:163], v[194:197], v[12:15]
	v_mfma_f32_16x16x32_bf16 v[114:117], v[156:159], v[172:175], v[114:117]
	v_mfma_f32_16x16x32_bf16 v[118:121], v[164:167], v[172:175], v[118:121]
	v_mfma_f32_16x16x32_bf16 v[110:113], v[156:159], v[180:183], v[110:113]
	v_mfma_f32_16x16x32_bf16 v[98:101], v[164:167], v[180:183], v[98:101]
	v_mfma_f32_16x16x32_bf16 v[70:73], v[156:159], v[190:193], v[70:73]
	v_mfma_f32_16x16x32_bf16 v[60:63], v[164:167], v[190:193], v[60:63]
	v_mfma_f32_16x16x32_bf16 v[20:23], v[156:159], v[198:201], v[20:23]
	v_mfma_f32_16x16x32_bf16 v[12:15], v[164:167], v[198:201], v[12:15]
	s_setprio 0
	s_barrier
	s_add_i32 s60, 0, 0x18000
	v_add_u32_e32 v64, s60, v134
	s_add_i32 s61, 0, 0x1c000
	ds_read_b128 v[136:139], v64
	ds_read_b128 v[140:143], v64 offset:1024
	ds_read_b128 v[144:147], v64 offset:2048
	ds_read_b128 v[148:151], v64 offset:3072
	v_add_u32_e32 v64, s61, v134
	ds_read_b128 v[152:155], v64
	ds_read_b128 v[156:159], v64 offset:1024
	ds_read_b128 v[160:163], v64 offset:2048
	ds_read_b128 v[164:167], v64 offset:3072
	s_add_u32 s58, s2, 0x100000
	v_mov_b32_e32 v64, v130
	s_mov_b32 m0, s49
	ds_read_b128 v[168:171], v135 offset:32768
	ds_read_b128 v[172:175], v135 offset:33792
	ds_read_b128 v[176:179], v135 offset:34816
	ds_read_b128 v[180:183], v135 offset:35840
	ds_read_b128 v[184:187], v135 offset:36864
	ds_read_b128 v[190:193], v135 offset:37888
	ds_read_b128 v[194:197], v135 offset:38912
	ds_read_b128 v[198:201], v135 offset:39936
	s_addc_u32 s59, s3, 0
	s_nop 0
	global_load_lds_dwordx4 v64, s[58:59]
	v_mov_b32_e32 v64, v132
	s_mov_b32 m0, s50
	s_nop 0
	global_load_lds_dwordx4 v64, s[58:59]
	s_waitcnt vmcnt(8)
	s_waitcnt lgkmcnt(0)
	s_barrier
	s_setprio 1
	s_waitcnt lgkmcnt(0)
	v_mfma_f32_16x16x32_bf16 v[48:51], v[136:139], v[168:171], v[48:51]
	v_mfma_f32_16x16x32_bf16 v[44:47], v[144:147], v[168:171], v[44:47]
	v_mfma_f32_16x16x32_bf16 v[4:7], v[136:139], v[176:179], v[4:7]
	v_mfma_f32_16x16x32_bf16 v[0:3], v[144:147], v[176:179], v[0:3]
	v_mfma_f32_16x16x32_bf16 v[36:39], v[136:139], v[184:187], v[36:39]
	v_mfma_f32_16x16x32_bf16 v[32:35], v[144:147], v[184:187], v[32:35]
	v_mfma_f32_16x16x32_bf16 v[78:81], v[136:139], v[194:197], v[78:81]
	v_mfma_f32_16x16x32_bf16 v[74:77], v[144:147], v[194:197], v[74:77]
	v_mfma_f32_16x16x32_bf16 v[48:51], v[140:143], v[172:175], v[48:51]
	v_mfma_f32_16x16x32_bf16 v[44:47], v[148:151], v[172:175], v[44:47]
	v_mfma_f32_16x16x32_bf16 v[4:7], v[140:143], v[180:183], v[4:7]
	v_mfma_f32_16x16x32_bf16 v[0:3], v[148:151], v[180:183], v[0:3]
	v_mfma_f32_16x16x32_bf16 v[36:39], v[140:143], v[190:193], v[36:39]
	v_mfma_f32_16x16x32_bf16 v[32:35], v[148:151], v[190:193], v[32:35]
	v_mfma_f32_16x16x32_bf16 v[78:81], v[140:143], v[198:201], v[78:81]
	v_mfma_f32_16x16x32_bf16 v[74:77], v[148:151], v[198:201], v[74:77]
	v_mfma_f32_16x16x32_bf16 v[16:19], v[152:155], v[168:171], v[16:19]
	v_mfma_f32_16x16x32_bf16 v[8:11], v[160:163], v[168:171], v[8:11]
	v_mfma_f32_16x16x32_bf16 v[24:27], v[152:155], v[176:179], v[24:27]
	v_mfma_f32_16x16x32_bf16 v[28:31], v[160:163], v[176:179], v[28:31]
	v_mfma_f32_16x16x32_bf16 v[56:59], v[152:155], v[184:187], v[56:59]
	v_mfma_f32_16x16x32_bf16 v[66:69], v[160:163], v[184:187], v[66:69]
	v_mfma_f32_16x16x32_bf16 v[86:89], v[152:155], v[194:197], v[86:89]
	v_mfma_f32_16x16x32_bf16 v[94:97], v[160:163], v[194:197], v[94:97]
	v_mfma_f32_16x16x32_bf16 v[16:19], v[156:159], v[172:175], v[16:19]
	v_mfma_f32_16x16x32_bf16 v[8:11], v[164:167], v[172:175], v[8:11]
	v_mfma_f32_16x16x32_bf16 v[24:27], v[156:159], v[180:183], v[24:27]
	v_mfma_f32_16x16x32_bf16 v[28:31], v[164:167], v[180:183], v[28:31]
	v_mfma_f32_16x16x32_bf16 v[56:59], v[156:159], v[190:193], v[56:59]
	v_mfma_f32_16x16x32_bf16 v[66:69], v[164:167], v[190:193], v[66:69]
	v_mfma_f32_16x16x32_bf16 v[86:89], v[156:159], v[198:201], v[86:89]
	v_mfma_f32_16x16x32_bf16 v[94:97], v[164:167], v[198:201], v[94:97]
	s_setprio 0
	s_barrier
	v_mov_b32_e32 v64, v130
	s_mov_b32 m0, s51
	v_lshl_add_u64 v[214:215], s[2:3], 0, v[64:65]
	v_lshl_add_u64 v[214:215], v[214:215], 0, s[24:25]
	v_mov_b32_e32 v64, v132
	global_load_lds_dwordx4 v[214:215], off
	s_mov_b32 m0, s52
	v_lshl_add_u64 v[214:215], s[2:3], 0, v[64:65]
	v_lshl_add_u64 v[214:215], v[214:215], 0, s[24:25]
	global_load_lds_dwordx4 v[214:215], off
	v_mov_b32_e32 v64, v131
	ds_read_b128 v[168:171], v135 offset:49152
	ds_read_b128 v[172:175], v135 offset:50176
	ds_read_b128 v[176:179], v135 offset:51200
	ds_read_b128 v[180:183], v135 offset:52224
	ds_read_b128 v[184:187], v135 offset:53248
	ds_read_b128 v[190:193], v135 offset:54272
	ds_read_b128 v[194:197], v135 offset:55296
	ds_read_b128 v[198:201], v135 offset:56320
	s_add_i32 s58, s60, s11
	v_lshl_add_u64 v[214:215], s[54:55], 0, v[64:65]
	v_lshl_add_u64 v[214:215], v[214:215], 0, s[24:25]
	s_mov_b32 m0, s58
	v_mov_b32_e32 v64, v133
	global_load_lds_dwordx4 v[214:215], off
	s_add_i32 m0, s58, 0x2000
	s_nop 0
	v_lshl_add_u64 v[214:215], s[54:55], 0, v[64:65]
	s_add_u32 s54, s54, 0x100080
	v_lshl_add_u64 v[214:215], v[214:215], 0, s[24:25]
	s_addc_u32 s55, s55, 0
	v_mov_b32_e32 v64, v131
	s_add_i32 s58, s61, s11
	global_load_lds_dwordx4 v[214:215], off
	s_mov_b32 m0, s58
	s_nop 0
	global_load_lds_dwordx4 v64, s[54:55]
	v_mov_b32_e32 v64, v133
	s_add_i32 m0, s58, 0x2000
	s_nop 0
	global_load_lds_dwordx4 v64, s[54:55]
	s_waitcnt vmcnt(8)
	s_waitcnt lgkmcnt(0)
	s_barrier
	s_setprio 1
	s_waitcnt lgkmcnt(0)
	v_mfma_f32_16x16x32_bf16 v[106:109], v[136:139], v[168:171], v[106:109]
	v_mfma_f32_16x16x32_bf16 v[102:105], v[144:147], v[168:171], v[102:105]
	v_mfma_f32_16x16x32_bf16 v[126:129], v[136:139], v[176:179], v[126:129]
	v_mfma_f32_16x16x32_bf16 v[122:125], v[144:147], v[176:179], v[122:125]
	v_mfma_f32_16x16x32_bf16 v[90:93], v[136:139], v[184:187], v[90:93]
	v_mfma_f32_16x16x32_bf16 v[82:85], v[144:147], v[184:187], v[82:85]
	v_mfma_f32_16x16x32_bf16 v[52:55], v[136:139], v[194:197], v[52:55]
	v_mfma_f32_16x16x32_bf16 v[40:43], v[144:147], v[194:197], v[40:43]
	v_mfma_f32_16x16x32_bf16 v[106:109], v[140:143], v[172:175], v[106:109]
	v_mfma_f32_16x16x32_bf16 v[102:105], v[148:151], v[172:175], v[102:105]
	v_mfma_f32_16x16x32_bf16 v[126:129], v[140:143], v[180:183], v[126:129]
	v_mfma_f32_16x16x32_bf16 v[122:125], v[148:151], v[180:183], v[122:125]
	v_mfma_f32_16x16x32_bf16 v[90:93], v[140:143], v[190:193], v[90:93]
	v_mfma_f32_16x16x32_bf16 v[82:85], v[148:151], v[190:193], v[82:85]
	v_mfma_f32_16x16x32_bf16 v[52:55], v[140:143], v[198:201], v[52:55]
	v_mfma_f32_16x16x32_bf16 v[40:43], v[148:151], v[198:201], v[40:43]
	v_mfma_f32_16x16x32_bf16 v[114:117], v[152:155], v[168:171], v[114:117]
	v_mfma_f32_16x16x32_bf16 v[118:121], v[160:163], v[168:171], v[118:121]
	v_mfma_f32_16x16x32_bf16 v[110:113], v[152:155], v[176:179], v[110:113]
	v_mfma_f32_16x16x32_bf16 v[98:101], v[160:163], v[176:179], v[98:101]
	v_mfma_f32_16x16x32_bf16 v[70:73], v[152:155], v[184:187], v[70:73]
	v_mfma_f32_16x16x32_bf16 v[60:63], v[160:163], v[184:187], v[60:63]
	v_mfma_f32_16x16x32_bf16 v[20:23], v[152:155], v[194:197], v[20:23]
	v_mfma_f32_16x16x32_bf16 v[12:15], v[160:163], v[194:197], v[12:15]
	v_mfma_f32_16x16x32_bf16 v[114:117], v[156:159], v[172:175], v[114:117]
	v_mfma_f32_16x16x32_bf16 v[118:121], v[164:167], v[172:175], v[118:121]
	v_mfma_f32_16x16x32_bf16 v[110:113], v[156:159], v[180:183], v[110:113]
	v_mfma_f32_16x16x32_bf16 v[98:101], v[164:167], v[180:183], v[98:101]
	v_mfma_f32_16x16x32_bf16 v[70:73], v[156:159], v[190:193], v[70:73]
	v_mfma_f32_16x16x32_bf16 v[60:63], v[164:167], v[190:193], v[60:63]
	v_mfma_f32_16x16x32_bf16 v[20:23], v[156:159], v[198:201], v[20:23]
	v_mfma_f32_16x16x32_bf16 v[12:15], v[164:167], v[198:201], v[12:15]
	s_setprio 0
	s_barrier
	s_add_i32 s57, s57, 2
	s_add_u32 s88, s88, 0x100
	s_addc_u32 s89, s89, 0
	s_cmp_gt_u32 s57, 61
	s_cbranch_scc0 .LBB0_695
	s_cmp_lt_u32 s48, 4
	s_cbranch_scc0 .LBB0_698
	s_barrier
